# K-loop: plus s_setprio 1 moved after first MFMA (a,b,c)
# speedup vs baseline: 1.0080x; 1.0080x over previous
; #define PG8_STAGE(bufoff, gbase, voff) do { _Pragma("unroll") for (int _i = 0; _i < 2; ++_i) \
;         __builtin_amdgcn_global_load_lds((const unsigned*)((const char*)(gbase) + (voff)[_i]), (LAS unsigned*)(lds + (bufoff) + ldsw + _i * 8192), 16, 0, 0); } while (0)
; #define PG8_LDA(dst, b, h) do { _Pragma("unroll") for (int m = 0; m < 4; ++m) _Pragma("unroll") for (int k = 0; k < 2; ++k) dst[m][k] = *(const LAS bf16x8*)(lds + PG8_SA(b, h) + aoff + m * 2048 + k * 1024); } while (0)
; #define PG8_LDB(dst, b, h) do { _Pragma("unroll") for (int n = 0; n < 2; ++n) _Pragma("unroll") for (int k = 0; k < 2; ++k) dst[n][k] = *(const LAS bf16x8*)(lds + PG8_SB(b, h) + boff + n * 2048 + k * 1024); } while (0)
; #define PG8_MMA(ai, bj, At, Bt) do { __builtin_amdgcn_s_setprio(1); _Pragma("unroll") for (int m = 0; m < 4; ++m) _Pragma("unroll") for (int n = 0; n < 2; ++n) _Pragma("unroll") for (int k = 0; k < 2; ++k) \
;         acc[ai][bj][m][n] = __builtin_amdgcn_mfma_f32_16x16x32_bf16(Bt[n][k], At[m][k], acc[ai][bj][m][n], 0, 0, 0); __builtin_amdgcn_s_setprio(0); } while (0)
; #define PG8_WAIT_L(n) asm volatile("s_waitcnt lgkmcnt(" #n ")" ::: "memory")
; #define PG8_BAR __builtin_amdgcn_s_barrier()
; #define PG8_SCHED __builtin_amdgcn_sched_barrier(0)
; template <class Epi>
; __device__ __forceinline__ void gemm_phase(LAS unsigned char* lds, const Gemm g, const StaticOrder& S, const Epi& E) {
;     ...
;             const bool last = (t == nt - 2);
;             const char* a1 = cA + (size_t)(t + 1) * kstep;
;             const char* a2 = last ? nA : cA + (size_t)(t + 2) * kstep; const char* b2 = last ? nB : cB + (size_t)(t + 2) * kstep;
;             const char* a3 = a2 + kstep; const char* b3 = b2 + kstep;
;             PG8_LDB(B0, 0, 0); PG8_SCHED; PG8_LDA(At, 0, 0); PG8_STAGE(PG8_SA(1, 1), a1 + hstepA, voffA);
;             PG8_WAIT_L(8); PG8_BAR; PG8_WAIT_L(0); PG8_MMA(0, 0, At, B0); PG8_BAR; PG8_SCHED;
;             PG8_LDB(B1, 0, 1); PG8_STAGE(PG8_SB(0, 0), b2, voffB);
;             PG8_BAR; PG8_WAIT_L(0); PG8_MMA(0, 1, At, B1); PG8_BAR;
;             PG8_LDA(At, 0, 1); PG8_STAGE(PG8_SA(0, 0), a2, voffA);
;             PG8_BAR; PG8_WAIT_L(0); PG8_MMA(1, 0, At, B0); PG8_BAR; PG8_SCHED;
.LBB0_141:
	s_add_u32 s24, s22, 0xfff84000
	s_addc_u32 s25, s23, -1
	s_cmp_eq_u32 s54, 28
	s_cselect_b32 s28, s49, s24
	s_cselect_b32 s29, s15, s25
	s_cselect_b32 s24, s50, s51
	s_cselect_b32 s25, s5, s52
	s_add_u32 s26, s28, 0x4000
	s_addc_u32 s27, s29, 0
	s_add_i32 s55, 0, 0x10000
	v_add_u32_e32 v148, s55, v134
	ds_read_b128 v[136:139], v148
	ds_read_b128 v[140:143], v148 offset:1024
	ds_read_b128 v[144:147], v148 offset:2048
	ds_read_b128 v[148:151], v148 offset:3072
	v_lshl_add_u64 v[188:189], s[22:23], 0, v[128:129]
	s_add_i32 m0, s37, 0xc000
	ds_read_b128 v[156:159], v135
	ds_read_b128 v[160:163], v135 offset:1024
	ds_read_b128 v[164:167], v135 offset:2048
	ds_read_b128 v[168:171], v135 offset:3072
	ds_read_b128 v[172:175], v135 offset:4096
	ds_read_b128 v[176:179], v135 offset:5120
	ds_read_b128 v[180:183], v135 offset:6144
	ds_read_b128 v[184:187], v135 offset:7168
	global_load_lds_dwordx4 v[188:189], off
	s_add_i32 m0, s37, 0xe000
	v_lshl_add_u64 v[188:189], s[22:23], 0, v[130:131]
	global_load_lds_dwordx4 v[188:189], off
	s_waitcnt lgkmcnt(8)
	s_barrier
	s_waitcnt lgkmcnt(0)
	v_mfma_f32_16x16x32_bf16 v[124:127], v[136:139], v[156:159], v[124:127]
	s_setprio 1
	v_mfma_f32_16x16x32_bf16 v[120:123], v[144:147], v[156:159], v[120:123]
	v_mfma_f32_16x16x32_bf16 v[108:111], v[136:139], v[164:167], v[108:111]
	v_mfma_f32_16x16x32_bf16 v[104:107], v[144:147], v[164:167], v[104:107]
	v_mfma_f32_16x16x32_bf16 v[92:95], v[136:139], v[172:175], v[92:95]
	v_mfma_f32_16x16x32_bf16 v[88:91], v[144:147], v[172:175], v[88:91]
	v_mfma_f32_16x16x32_bf16 v[76:79], v[136:139], v[180:183], v[76:79]
	v_mfma_f32_16x16x32_bf16 v[72:75], v[144:147], v[180:183], v[72:75]
	v_mfma_f32_16x16x32_bf16 v[124:127], v[140:143], v[160:163], v[124:127]
	v_mfma_f32_16x16x32_bf16 v[120:123], v[148:151], v[160:163], v[120:123]
	v_mfma_f32_16x16x32_bf16 v[108:111], v[140:143], v[168:171], v[108:111]
	v_mfma_f32_16x16x32_bf16 v[104:107], v[148:151], v[168:171], v[104:107]
	v_mfma_f32_16x16x32_bf16 v[92:95], v[140:143], v[176:179], v[92:95]
	v_mfma_f32_16x16x32_bf16 v[88:91], v[148:151], v[176:179], v[88:91]
	v_mfma_f32_16x16x32_bf16 v[76:79], v[140:143], v[184:187], v[76:79]
	s_setprio 0
	v_mfma_f32_16x16x32_bf16 v[72:75], v[148:151], v[184:187], v[72:75]
	s_barrier
	s_add_i32 s58, 0, 0x14000
	s_add_i32 s55, s55, s36
	v_add_u32_e32 v152, s58, v134
	v_lshl_add_u64 v[204:205], s[24:25], 0, v[128:129]
	s_mov_b32 m0, s55
	ds_read_b128 v[188:191], v152
	ds_read_b128 v[192:195], v152 offset:1024
	ds_read_b128 v[196:199], v152 offset:2048
	ds_read_b128 v[200:203], v152 offset:3072
	global_load_lds_dwordx4 v[204:205], off
	s_add_i32 m0, s55, 0x2000
	v_lshl_add_u64 v[204:205], s[24:25], 0, v[130:131]
	global_load_lds_dwordx4 v[204:205], off
	s_barrier
	s_waitcnt lgkmcnt(0)
	v_mfma_f32_16x16x32_bf16 v[116:119], v[188:191], v[156:159], v[116:119]
	s_setprio 1
	v_mfma_f32_16x16x32_bf16 v[112:115], v[196:199], v[156:159], v[112:115]
	s_mov_b32 m0, s37
	v_lshl_add_u64 v[204:205], s[28:29], 0, v[128:129]
	v_mfma_f32_16x16x32_bf16 v[100:103], v[188:191], v[164:167], v[100:103]
	v_mfma_f32_16x16x32_bf16 v[96:99], v[196:199], v[164:167], v[96:99]
	v_mfma_f32_16x16x32_bf16 v[84:87], v[188:191], v[172:175], v[84:87]
	v_mfma_f32_16x16x32_bf16 v[80:83], v[196:199], v[172:175], v[80:83]
	v_mfma_f32_16x16x32_bf16 v[68:71], v[188:191], v[180:183], v[68:71]
	v_mfma_f32_16x16x32_bf16 v[64:67], v[196:199], v[180:183], v[64:67]
	v_mfma_f32_16x16x32_bf16 v[116:119], v[192:195], v[160:163], v[116:119]
	v_mfma_f32_16x16x32_bf16 v[112:115], v[200:203], v[160:163], v[112:115]
	v_mfma_f32_16x16x32_bf16 v[100:103], v[192:195], v[168:171], v[100:103]
	v_mfma_f32_16x16x32_bf16 v[96:99], v[200:203], v[168:171], v[96:99]
	v_mfma_f32_16x16x32_bf16 v[84:87], v[192:195], v[176:179], v[84:87]
	v_mfma_f32_16x16x32_bf16 v[80:83], v[200:203], v[176:179], v[80:83]
	v_mfma_f32_16x16x32_bf16 v[68:71], v[192:195], v[184:187], v[68:71]
	s_setprio 0
	v_mfma_f32_16x16x32_bf16 v[64:67], v[200:203], v[184:187], v[64:67]
	s_barrier
	ds_read_b128 v[156:159], v135 offset:16384
	ds_read_b128 v[160:163], v135 offset:17408
	ds_read_b128 v[164:167], v135 offset:18432
	ds_read_b128 v[168:171], v135 offset:19456
	ds_read_b128 v[172:175], v135 offset:20480
	ds_read_b128 v[176:179], v135 offset:21504
	ds_read_b128 v[180:183], v135 offset:22528
	ds_read_b128 v[184:187], v135 offset:23552
	global_load_lds_dwordx4 v[204:205], off
	s_mov_b32 m0, s38
	v_lshl_add_u64 v[204:205], s[28:29], 0, v[130:131]
	global_load_lds_dwordx4 v[204:205], off
	s_barrier
	s_waitcnt lgkmcnt(0)
	v_mfma_f32_16x16x32_bf16 v[60:63], v[136:139], v[156:159], v[60:63]
	s_setprio 1
	v_mfma_f32_16x16x32_bf16 v[56:59], v[144:147], v[156:159], v[56:59]
	v_mfma_f32_16x16x32_bf16 v[44:47], v[136:139], v[164:167], v[44:47]
	v_mfma_f32_16x16x32_bf16 v[40:43], v[144:147], v[164:167], v[40:43]
	v_mfma_f32_16x16x32_bf16 v[28:31], v[136:139], v[172:175], v[28:31]
	v_mfma_f32_16x16x32_bf16 v[24:27], v[144:147], v[172:175], v[24:27]
	v_mfma_f32_16x16x32_bf16 v[12:15], v[136:139], v[180:183], v[12:15]
	v_mfma_f32_16x16x32_bf16 v[8:11], v[144:147], v[180:183], v[8:11]
	v_mfma_f32_16x16x32_bf16 v[60:63], v[140:143], v[160:163], v[60:63]
	v_mfma_f32_16x16x32_bf16 v[56:59], v[148:151], v[160:163], v[56:59]
	v_mfma_f32_16x16x32_bf16 v[44:47], v[140:143], v[168:171], v[44:47]
	v_mfma_f32_16x16x32_bf16 v[40:43], v[148:151], v[168:171], v[40:43]
	v_mfma_f32_16x16x32_bf16 v[28:31], v[140:143], v[176:179], v[28:31]
	v_mfma_f32_16x16x32_bf16 v[24:27], v[148:151], v[176:179], v[24:27]
	v_mfma_f32_16x16x32_bf16 v[12:15], v[140:143], v[184:187], v[12:15]
	s_setprio 0
	v_mfma_f32_16x16x32_bf16 v[8:11], v[148:151], v[184:187], v[8:11]
	s_barrier
; #define PG8_STAGE(bufoff, gbase, voff) do { _Pragma("unroll") for (int _i = 0; _i < 2; ++_i) \
;         __builtin_amdgcn_global_load_lds((const unsigned*)((const char*)(gbase) + (voff)[_i]), (LAS unsigned*)(lds + (bufoff) + ldsw + _i * 8192), 16, 0, 0); } while (0)
; #define PG8_LDA(dst, b, h) do { _Pragma("unroll") for (int m = 0; m < 4; ++m) _Pragma("unroll") for (int k = 0; k < 2; ++k) dst[m][k] = *(const LAS bf16x8*)(lds + PG8_SA(b, h) + aoff + m * 2048 + k * 1024); } while (0)
; #define PG8_LDB(dst, b, h) do { _Pragma("unroll") for (int n = 0; n < 2; ++n) _Pragma("unroll") for (int k = 0; k < 2; ++k) dst[n][k] = *(const LAS bf16x8*)(lds + PG8_SB(b, h) + boff + n * 2048 + k * 1024); } while (0)
; #define PG8_MMA(ai, bj, At, Bt) do { __builtin_amdgcn_s_setprio(1); _Pragma("unroll") for (int m = 0; m < 4; ++m) _Pragma("unroll") for (int n = 0; n < 2; ++n) _Pragma("unroll") for (int k = 0; k < 2; ++k) \
;         acc[ai][bj][m][n] = __builtin_amdgcn_mfma_f32_16x16x32_bf16(Bt[n][k], At[m][k], acc[ai][bj][m][n], 0, 0, 0); __builtin_amdgcn_s_setprio(0); } while (0)
; #define PG8_WAIT_V(n) asm volatile("s_waitcnt vmcnt(" #n ")" ::: "memory")
; #define PG8_WAIT_L(n) asm volatile("s_waitcnt lgkmcnt(" #n ")" ::: "memory")
; #define PG8_BAR __builtin_amdgcn_s_barrier()
; #define PG8_SCHED __builtin_amdgcn_sched_barrier(0)
; template <class Epi>
; __device__ __forceinline__ void gemm_phase(LAS unsigned char* lds, const Gemm g, const StaticOrder& S, const Epi& E) {
;     ...
;             PG8_STAGE(PG8_SB(0, 1), b2 + hstepB, voffB);
;             PG8_WAIT_V(6); PG8_BAR; PG8_MMA(1, 1, At, B1); PG8_BAR;
;             PG8_LDB(B0, 1, 0); PG8_SCHED; PG8_LDA(At, 1, 0); PG8_STAGE(PG8_SA(0, 1), a2 + hstepA, voffA);
;             PG8_WAIT_L(8); PG8_BAR; PG8_WAIT_L(0); PG8_MMA(0, 0, At, B0); PG8_BAR; PG8_SCHED;
;             PG8_LDB(B1, 1, 1); PG8_STAGE(PG8_SB(1, 0), b3, voffB);
;             PG8_BAR; PG8_WAIT_L(0); PG8_MMA(0, 1, At, B1); PG8_BAR;
;             PG8_LDA(At, 1, 1); PG8_STAGE(PG8_SA(1, 0), a3, voffA);
	s_add_u32 s56, s24, 0x80000
	s_addc_u32 s57, s25, 0
	s_add_i32 s55, s58, s36
	s_mov_b32 m0, s55
	v_lshl_add_u64 v[136:137], s[56:57], 0, v[128:129]
	global_load_lds_dwordx4 v[136:137], off
	s_add_i32 m0, s55, 0x2000
	v_lshl_add_u64 v[136:137], s[56:57], 0, v[130:131]
	global_load_lds_dwordx4 v[136:137], off
	s_waitcnt vmcnt(6)
	s_barrier
	v_mfma_f32_16x16x32_bf16 v[52:55], v[188:191], v[156:159], v[52:55]
	s_setprio 1
	v_mfma_f32_16x16x32_bf16 v[48:51], v[196:199], v[156:159], v[48:51]
	s_add_i32 s55, 0, 0x18000
	v_add_u32_e32 v148, s55, v134
	v_mfma_f32_16x16x32_bf16 v[36:39], v[188:191], v[164:167], v[36:39]
	v_mfma_f32_16x16x32_bf16 v[32:35], v[196:199], v[164:167], v[32:35]
	v_mfma_f32_16x16x32_bf16 v[20:23], v[188:191], v[172:175], v[20:23]
	v_mfma_f32_16x16x32_bf16 v[16:19], v[196:199], v[172:175], v[16:19]
	v_mfma_f32_16x16x32_bf16 v[4:7], v[188:191], v[180:183], v[4:7]
	v_mfma_f32_16x16x32_bf16 v[0:3], v[196:199], v[180:183], v[0:3]
	v_mfma_f32_16x16x32_bf16 v[52:55], v[192:195], v[160:163], v[52:55]
	v_mfma_f32_16x16x32_bf16 v[48:51], v[200:203], v[160:163], v[48:51]
	v_mfma_f32_16x16x32_bf16 v[36:39], v[192:195], v[168:171], v[36:39]
	v_mfma_f32_16x16x32_bf16 v[32:35], v[200:203], v[168:171], v[32:35]
	v_mfma_f32_16x16x32_bf16 v[20:23], v[192:195], v[176:179], v[20:23]
	v_mfma_f32_16x16x32_bf16 v[16:19], v[200:203], v[176:179], v[16:19]
	v_mfma_f32_16x16x32_bf16 v[4:7], v[192:195], v[184:187], v[4:7]
	s_setprio 0
	v_mfma_f32_16x16x32_bf16 v[0:3], v[200:203], v[184:187], v[0:3]
	s_barrier
	ds_read_b128 v[136:139], v148
	ds_read_b128 v[140:143], v148 offset:1024
	ds_read_b128 v[144:147], v148 offset:2048
	ds_read_b128 v[148:151], v148 offset:3072
	s_add_u32 s28, s28, 0x80000
	s_addc_u32 s29, s29, 0
	s_mov_b32 m0, s39
	v_lshl_add_u64 v[188:189], s[28:29], 0, v[128:129]
	ds_read_b128 v[156:159], v135 offset:32768
	ds_read_b128 v[160:163], v135 offset:33792
	ds_read_b128 v[164:167], v135 offset:34816
	ds_read_b128 v[168:171], v135 offset:35840
	ds_read_b128 v[172:175], v135 offset:36864
	ds_read_b128 v[176:179], v135 offset:37888
	ds_read_b128 v[180:183], v135 offset:38912
	ds_read_b128 v[184:187], v135 offset:39936
	global_load_lds_dwordx4 v[188:189], off
	s_mov_b32 m0, s40
	v_lshl_add_u64 v[188:189], s[28:29], 0, v[130:131]
	global_load_lds_dwordx4 v[188:189], off
	s_waitcnt lgkmcnt(8)
	s_barrier
	s_waitcnt lgkmcnt(0)
	v_mfma_f32_16x16x32_bf16 v[124:127], v[136:139], v[156:159], v[124:127]
	s_setprio 1
	v_mfma_f32_16x16x32_bf16 v[120:123], v[144:147], v[156:159], v[120:123]
	v_mfma_f32_16x16x32_bf16 v[108:111], v[136:139], v[164:167], v[108:111]
	v_mfma_f32_16x16x32_bf16 v[104:107], v[144:147], v[164:167], v[104:107]
	v_mfma_f32_16x16x32_bf16 v[92:95], v[136:139], v[172:175], v[92:95]
	v_mfma_f32_16x16x32_bf16 v[88:91], v[144:147], v[172:175], v[88:91]
	v_mfma_f32_16x16x32_bf16 v[76:79], v[136:139], v[180:183], v[76:79]
	v_mfma_f32_16x16x32_bf16 v[72:75], v[144:147], v[180:183], v[72:75]
	v_mfma_f32_16x16x32_bf16 v[124:127], v[140:143], v[160:163], v[124:127]
	v_mfma_f32_16x16x32_bf16 v[120:123], v[148:151], v[160:163], v[120:123]
	v_mfma_f32_16x16x32_bf16 v[108:111], v[140:143], v[168:171], v[108:111]
	v_mfma_f32_16x16x32_bf16 v[104:107], v[148:151], v[168:171], v[104:107]
	v_mfma_f32_16x16x32_bf16 v[92:95], v[140:143], v[176:179], v[92:95]
	v_mfma_f32_16x16x32_bf16 v[88:91], v[148:151], v[176:179], v[88:91]
	v_mfma_f32_16x16x32_bf16 v[76:79], v[140:143], v[184:187], v[76:79]
	s_setprio 0
	v_mfma_f32_16x16x32_bf16 v[72:75], v[148:151], v[184:187], v[72:75]
	s_barrier
	s_add_i32 s56, 0, 0x1c000
	s_add_u32 s28, s24, 0x4000
	s_addc_u32 s29, s25, 0
	s_add_i32 s55, s55, s36
	v_add_u32_e32 v152, s56, v134
	v_lshl_add_u64 v[204:205], s[28:29], 0, v[128:129]
	s_mov_b32 m0, s55
	ds_read_b128 v[188:191], v152
	ds_read_b128 v[192:195], v152 offset:1024
	ds_read_b128 v[196:199], v152 offset:2048
	ds_read_b128 v[200:203], v152 offset:3072
	global_load_lds_dwordx4 v[204:205], off
	s_add_i32 m0, s55, 0x2000
	v_lshl_add_u64 v[204:205], s[28:29], 0, v[130:131]
	global_load_lds_dwordx4 v[204:205], off
	s_barrier
	s_waitcnt lgkmcnt(0)
	v_mfma_f32_16x16x32_bf16 v[116:119], v[188:191], v[156:159], v[116:119]
	s_setprio 1
	v_mfma_f32_16x16x32_bf16 v[112:115], v[196:199], v[156:159], v[112:115]
	s_mov_b32 m0, s43
	v_lshl_add_u64 v[204:205], s[26:27], 0, v[128:129]
	v_mfma_f32_16x16x32_bf16 v[100:103], v[188:191], v[164:167], v[100:103]
	v_mfma_f32_16x16x32_bf16 v[96:99], v[196:199], v[164:167], v[96:99]
	v_mfma_f32_16x16x32_bf16 v[84:87], v[188:191], v[172:175], v[84:87]
	v_mfma_f32_16x16x32_bf16 v[80:83], v[196:199], v[172:175], v[80:83]
	v_mfma_f32_16x16x32_bf16 v[68:71], v[188:191], v[180:183], v[68:71]
	v_mfma_f32_16x16x32_bf16 v[64:67], v[196:199], v[180:183], v[64:67]
	v_mfma_f32_16x16x32_bf16 v[116:119], v[192:195], v[160:163], v[116:119]
	v_mfma_f32_16x16x32_bf16 v[112:115], v[200:203], v[160:163], v[112:115]
	v_mfma_f32_16x16x32_bf16 v[100:103], v[192:195], v[168:171], v[100:103]
	v_mfma_f32_16x16x32_bf16 v[96:99], v[200:203], v[168:171], v[96:99]
	v_mfma_f32_16x16x32_bf16 v[84:87], v[192:195], v[176:179], v[84:87]
	v_mfma_f32_16x16x32_bf16 v[80:83], v[200:203], v[176:179], v[80:83]
	v_mfma_f32_16x16x32_bf16 v[68:71], v[192:195], v[184:187], v[68:71]
	s_setprio 0
	v_mfma_f32_16x16x32_bf16 v[64:67], v[200:203], v[184:187], v[64:67]
	s_barrier
	ds_read_b128 v[156:159], v135 offset:49152
	ds_read_b128 v[160:163], v135 offset:50176
	ds_read_b128 v[164:167], v135 offset:51200
	ds_read_b128 v[168:171], v135 offset:52224
	ds_read_b128 v[172:175], v135 offset:53248
	ds_read_b128 v[176:179], v135 offset:54272
	ds_read_b128 v[180:183], v135 offset:55296
	ds_read_b128 v[184:187], v135 offset:56320
	global_load_lds_dwordx4 v[204:205], off
	s_mov_b32 m0, s44
	v_lshl_add_u64 v[204:205], s[26:27], 0, v[130:131]
	global_load_lds_dwordx4 v[204:205], off
	s_barrier
; __device__ __forceinline__ unsigned cvt_pk_bf16(float lo, float hi) { unsigned r; asm volatile("v_cvt_pk_bf16_f32 %0, %1, %2" : "=v"(r) : "v"(lo), "v"(hi)); return r; }
; #define PG8_STAGE(bufoff, gbase, voff) do { _Pragma("unroll") for (int _i = 0; _i < 2; ++_i) \
;         __builtin_amdgcn_global_load_lds((const unsigned*)((const char*)(gbase) + (voff)[_i]), (LAS unsigned*)(lds + (bufoff) + ldsw + _i * 8192), 16, 0, 0); } while (0)
; #define PG8_MMA(ai, bj, At, Bt) do { __builtin_amdgcn_s_setprio(1); _Pragma("unroll") for (int m = 0; m < 4; ++m) _Pragma("unroll") for (int n = 0; n < 2; ++n) _Pragma("unroll") for (int k = 0; k < 2; ++k) \
;         acc[ai][bj][m][n] = __builtin_amdgcn_mfma_f32_16x16x32_bf16(Bt[n][k], At[m][k], acc[ai][bj][m][n], 0, 0, 0); __builtin_amdgcn_s_setprio(0); } while (0)
; #define PG8_WAIT_V(n) asm volatile("s_waitcnt vmcnt(" #n ")" ::: "memory")
; #define PG8_WAIT_L(n) asm volatile("s_waitcnt lgkmcnt(" #n ")" ::: "memory")
; #define PG8_BAR __builtin_amdgcn_s_barrier()
; #define PG8_SCHED __builtin_amdgcn_sched_barrier(0)
; template <class Epi>
; __device__ __forceinline__ void gemm_phase(LAS unsigned char* lds, const Gemm g, const StaticOrder& S, const Epi& E) {
;     ...
;             PG8_BAR; PG8_WAIT_L(0); PG8_MMA(1, 0, At, B0); PG8_BAR; PG8_SCHED;
;             PG8_STAGE(PG8_SB(1, 1), b3 + hstepB, voffB);
;             PG8_WAIT_V(6); PG8_BAR; PG8_MMA(1, 1, At, B1); PG8_BAR;
;     __device__ __forceinline__ void operator()(const f32x4 (&acc)[2][2][4][2], const Unit& u, int wr, int wc, int fr, int fq) const {
;         const int row0 = u.pm * BM + wr * 64 + fr, col0 = u.pn * BM + wc * 32 + 8 * fq;
; #pragma unroll
;         for (int ai = 0; ai < 2; ++ai)
; #pragma unroll
;             for (int m = 0; m < 4; ++m) {
;                 const int rowi = row0 + ai * HALF + m * 16;
; #pragma unroll
;                 for (int bj = 0; bj < 2; ++bj) {
;                     f32x4 v0 = acc[ai][bj][m][0], v1 = acc[ai][bj][m][1];
; #pragma unroll
;                     for (int j = 0; j < 4; ++j) { const float a = fmaxf(v0[j], 0.f), b = fmaxf(v1[j], 0.f); v0[j] = a * a; v1[j] = b * b; }
;                     u32x4 w; w.x = cvt_pk_bf16(v0[0], v0[1]); w.y = cvt_pk_bf16(v0[2], v0[3]); w.z = cvt_pk_bf16(v1[0], v1[1]); w.w = cvt_pk_bf16(v1[2], v1[3]);
;                     *(u32x4*)(O + tiled_off(rowi, col0 + bj * HALF, DFF / 64)) = w;
	s_waitcnt lgkmcnt(0)
	v_mfma_f32_16x16x32_bf16 v[60:63], v[136:139], v[156:159], v[60:63]
	s_setprio 1
	v_mfma_f32_16x16x32_bf16 v[56:59], v[144:147], v[156:159], v[56:59]
	v_mfma_f32_16x16x32_bf16 v[44:47], v[136:139], v[164:167], v[44:47]
	v_mfma_f32_16x16x32_bf16 v[40:43], v[144:147], v[164:167], v[40:43]
	v_mfma_f32_16x16x32_bf16 v[28:31], v[136:139], v[172:175], v[28:31]
	v_mfma_f32_16x16x32_bf16 v[24:27], v[144:147], v[172:175], v[24:27]
	v_mfma_f32_16x16x32_bf16 v[12:15], v[136:139], v[180:183], v[12:15]
	v_mfma_f32_16x16x32_bf16 v[8:11], v[144:147], v[180:183], v[8:11]
	v_mfma_f32_16x16x32_bf16 v[60:63], v[140:143], v[160:163], v[60:63]
	v_mfma_f32_16x16x32_bf16 v[56:59], v[148:151], v[160:163], v[56:59]
	v_mfma_f32_16x16x32_bf16 v[44:47], v[140:143], v[168:171], v[44:47]
	v_mfma_f32_16x16x32_bf16 v[40:43], v[148:151], v[168:171], v[40:43]
	v_mfma_f32_16x16x32_bf16 v[28:31], v[140:143], v[176:179], v[28:31]
	v_mfma_f32_16x16x32_bf16 v[24:27], v[148:151], v[176:179], v[24:27]
	v_mfma_f32_16x16x32_bf16 v[12:15], v[140:143], v[184:187], v[12:15]
	s_setprio 0
	v_mfma_f32_16x16x32_bf16 v[8:11], v[148:151], v[184:187], v[8:11]
	s_barrier
	s_add_u32 s24, s24, 0x84000
	s_addc_u32 s25, s25, 0
	s_add_i32 s26, s56, s36
	s_mov_b32 m0, s26
	v_lshl_add_u64 v[136:137], s[24:25], 0, v[128:129]
	global_load_lds_dwordx4 v[136:137], off
	s_add_i32 m0, s26, 0x2000
	v_lshl_add_u64 v[136:137], s[24:25], 0, v[130:131]
	global_load_lds_dwordx4 v[136:137], off
	s_waitcnt vmcnt(6)
	s_barrier
	v_mfma_f32_16x16x32_bf16 v[52:55], v[188:191], v[156:159], v[52:55]
	s_setprio 1
	v_mfma_f32_16x16x32_bf16 v[48:51], v[196:199], v[156:159], v[48:51]
	s_add_i32 s54, s54, 2
	s_add_u32 s22, s22, 0x8000
	s_addc_u32 s23, s23, 0
	s_add_u32 s51, s51, 0x8000
	s_addc_u32 s52, s52, 0
	v_mfma_f32_16x16x32_bf16 v[36:39], v[188:191], v[164:167], v[36:39]
	v_mfma_f32_16x16x32_bf16 v[32:35], v[196:199], v[164:167], v[32:35]
	v_mfma_f32_16x16x32_bf16 v[20:23], v[188:191], v[172:175], v[20:23]
	v_mfma_f32_16x16x32_bf16 v[16:19], v[196:199], v[172:175], v[16:19]
	v_mfma_f32_16x16x32_bf16 v[4:7], v[188:191], v[180:183], v[4:7]
	v_mfma_f32_16x16x32_bf16 v[0:3], v[196:199], v[180:183], v[0:3]
	v_mfma_f32_16x16x32_bf16 v[52:55], v[192:195], v[160:163], v[52:55]
	v_mfma_f32_16x16x32_bf16 v[48:51], v[200:203], v[160:163], v[48:51]
	v_mfma_f32_16x16x32_bf16 v[36:39], v[192:195], v[168:171], v[36:39]
	v_mfma_f32_16x16x32_bf16 v[32:35], v[200:203], v[168:171], v[32:35]
	v_mfma_f32_16x16x32_bf16 v[20:23], v[192:195], v[176:179], v[20:23]
	v_mfma_f32_16x16x32_bf16 v[16:19], v[200:203], v[176:179], v[16:19]
	v_mfma_f32_16x16x32_bf16 v[4:7], v[192:195], v[184:187], v[4:7]
	s_cmp_gt_u32 s54, 29
	s_setprio 0
	v_mfma_f32_16x16x32_bf16 v[0:3], v[200:203], v[184:187], v[0:3]
	s_barrier
	s_cbranch_scc0 .LBB0_141
	s_lshl_b32 s24, s20, 8
	s_lshl_b32 s5, s21, 8
	s_add_i32 s24, s24, s41
	s_or_b32 s5, s5, s42
	s_and_b32 s22, s24, 0xffffff80
	s_ashr_i32 s5, s5, 6
	s_add_i32 s20, s22, s5
	s_ashr_i32 s21, s20, 31
	v_max_f32_e32 v120, 0, v120
	s_lshl_b64 s[20:21], s[20:21], 14
	v_readlane_b32 s26, v252, 57
	v_or_b32_e32 v136, s24, v132
	v_mul_f32_e32 v140, v120, v120
	v_max_f32_e32 v121, 0, v121
	v_max_f32_e32 v122, 0, v122
	v_readlane_b32 s27, v252, 58
	s_add_u32 s20, s26, s20
	v_lshlrev_b32_e32 v137, 6, v136
	s_movk_i32 s28, 0x3c0
	v_lshlrev_b32_e32 v138, 2, v136
	v_max_f32_e32 v120, 0, v125
	v_mul_f32_e32 v125, v121, v121
	v_max_f32_e32 v121, v126, v126
	v_mul_f32_e32 v126, v122, v122
	s_addc_u32 s21, s27, s21
	s_or_b32 s15, s5, 2
	v_and_or_b32 v137, v137, s28, v133
	v_and_b32_e32 v138, 32, v138
	v_max_f32_e32 v124, 0, v124
	v_mul_f32_e32 v120, v120, v120
	v_max_f32_e32 v121, 0, v121
	v_max_f32_e32 v122, 0, v127
	v_max_f32_e32 v123, 0, v123
	s_add_i32 s22, s15, s22
	v_bitop3_b32 v139, v137, s46, v138 bitop3:0xde
	v_mul_f32_e32 v124, v124, v124
	v_mul_f32_e32 v121, v121, v121
	v_mul_f32_e32 v122, v122, v122
	v_mul_f32_e32 v123, v123, v123
	v_cvt_pk_bf16_f32 v120, v124, v120
	v_max_f32_e32 v112, 0, v112
	v_max_f32_e32 v113, 0, v113
	s_ashr_i32 s23, s22, 31
	v_cvt_pk_bf16_f32 v121, v121, v122
	v_cvt_pk_bf16_f32 v122, v140, v125
	v_cvt_pk_bf16_f32 v123, v126, v123
	global_store_dwordx4 v139, v[120:123], s[20:21]
	v_max_f32_e32 v114, 0, v114
	s_lshl_b64 s[22:23], s[22:23], 14
	v_mul_f32_e32 v120, v112, v112
	v_max_f32_e32 v112, v117, v117
	v_mul_f32_e32 v117, v113, v113
	v_max_f32_e32 v112, 0, v112
	v_max_f32_e32 v113, 0, v118
	v_mul_f32_e32 v118, v114, v114
	s_add_u32 s22, s26, s22
	v_max_f32_e32 v116, 0, v116
	v_mul_f32_e32 v112, v112, v112
	v_mul_f32_e32 v113, v113, v113
	v_max_f32_e32 v114, 0, v119
	v_max_f32_e32 v115, 0, v115
	s_addc_u32 s23, s27, s23
	s_or_b32 s25, s24, 16
	v_mul_f32_e32 v116, v116, v116
	v_mul_f32_e32 v114, v114, v114
	v_mul_f32_e32 v115, v115, v115
	v_cvt_pk_bf16_f32 v112, v116, v112
	v_cvt_pk_bf16_f32 v113, v113, v114
	s_lshr_b32 s25, s25, 3
	v_max_f32_e32 v104, 0, v104
	v_cvt_pk_bf16_f32 v114, v120, v117
	v_cvt_pk_bf16_f32 v115, v118, v115
	global_store_dwordx4 v139, v[112:115], s[22:23]
	s_and_b32 s25, s25, 10
	v_max_f32_e32 v105, 0, v105
	v_mul_f32_e32 v113, v104, v104
	v_max_f32_e32 v106, 0, v106
	s_or_b32 s25, s25, s45
	v_max_f32_e32 v104, 0, v109
	v_mul_f32_e32 v109, v105, v105
	v_max_f32_e32 v105, v110, v110
	v_mul_f32_e32 v110, v106, v106
	s_lshl_b32 s25, s25, 10
	v_max_f32_e32 v108, 0, v108
	v_mul_f32_e32 v104, v104, v104
	v_max_f32_e32 v105, 0, v105
	v_max_f32_e32 v106, 0, v111
	v_max_f32_e32 v107, 0, v107
	v_bitop3_b32 v112, v137, s25, v138 bitop3:0xde
	v_mul_f32_e32 v108, v108, v108
	v_mul_f32_e32 v105, v105, v105
	v_mul_f32_e32 v106, v106, v106
	v_mul_f32_e32 v107, v107, v107
; __device__ __forceinline__ unsigned cvt_pk_bf16(float lo, float hi) { unsigned r; asm volatile("v_cvt_pk_bf16_f32 %0, %1, %2" : "=v"(r) : "v"(lo), "v"(hi)); return r; }
;     __device__ __forceinline__ void operator()(const f32x4 (&acc)[2][2][4][2], const Unit& u, int wr, int wc, int fr, int fq) const {
;         const int row0 = u.pm * BM + wr * 64 + fr, col0 = u.pn * BM + wc * 32 + 8 * fq;
; #pragma unroll
;         for (int ai = 0; ai < 2; ++ai)
; #pragma unroll
;             for (int m = 0; m < 4; ++m) {
;                 const int rowi = row0 + ai * HALF + m * 16;
; #pragma unroll
;                 for (int bj = 0; bj < 2; ++bj) {
;                     f32x4 v0 = acc[ai][bj][m][0], v1 = acc[ai][bj][m][1];
; #pragma unroll
;                     for (int j = 0; j < 4; ++j) { const float a = fmaxf(v0[j], 0.f), b = fmaxf(v1[j], 0.f); v0[j] = a * a; v1[j] = b * b; }
;                     u32x4 w; w.x = cvt_pk_bf16(v0[0], v0[1]); w.y = cvt_pk_bf16(v0[2], v0[3]); w.z = cvt_pk_bf16(v1[0], v1[1]); w.w = cvt_pk_bf16(v1[2], v1[3]);
;                     *(u32x4*)(O + tiled_off(rowi, col0 + bj * HALF, DFF / 64)) = w;
	v_cvt_pk_bf16_f32 v104, v108, v104
	v_max_f32_e32 v96, 0, v96
	v_max_f32_e32 v97, 0, v97
	v_cvt_pk_bf16_f32 v105, v105, v106
	v_cvt_pk_bf16_f32 v106, v113, v109
	v_cvt_pk_bf16_f32 v107, v110, v107
	global_store_dwordx4 v112, v[104:107], s[20:21]
	s_nop 0
	v_max_f32_e32 v98, 0, v98
	v_mul_f32_e32 v104, v96, v96
	v_max_f32_e32 v96, v101, v101
	v_mul_f32_e32 v101, v97, v97
	v_max_f32_e32 v96, 0, v96
	v_max_f32_e32 v97, 0, v102
	v_mul_f32_e32 v102, v98, v98
	v_max_f32_e32 v100, 0, v100
	v_mul_f32_e32 v96, v96, v96
	v_mul_f32_e32 v97, v97, v97
	v_max_f32_e32 v98, 0, v103
	v_max_f32_e32 v99, 0, v99
	s_or_b32 s25, s24, 32
	v_mul_f32_e32 v100, v100, v100
	v_mul_f32_e32 v98, v98, v98
	v_mul_f32_e32 v99, v99, v99
	v_cvt_pk_bf16_f32 v96, v100, v96
	v_cvt_pk_bf16_f32 v97, v97, v98
	s_lshr_b32 s25, s25, 3
	v_max_f32_e32 v88, 0, v88
	v_cvt_pk_bf16_f32 v98, v104, v101
	v_cvt_pk_bf16_f32 v99, v102, v99
	global_store_dwordx4 v112, v[96:99], s[22:23]
	s_and_b32 s25, s25, 12
	v_max_f32_e32 v89, 0, v89
	v_mul_f32_e32 v97, v88, v88
	v_max_f32_e32 v90, 0, v90
	s_or_b32 s25, s25, s45
	v_max_f32_e32 v88, 0, v93
	v_mul_f32_e32 v93, v89, v89
	v_max_f32_e32 v89, v94, v94
	v_mul_f32_e32 v94, v90, v90
	s_lshl_b32 s25, s25, 10
	v_max_f32_e32 v92, 0, v92
	v_mul_f32_e32 v88, v88, v88
	v_max_f32_e32 v89, 0, v89
	v_max_f32_e32 v90, 0, v95
	v_max_f32_e32 v91, 0, v91
	v_bitop3_b32 v96, v137, s25, v138 bitop3:0xde
	v_mul_f32_e32 v92, v92, v92
	v_mul_f32_e32 v89, v89, v89
	v_mul_f32_e32 v90, v90, v90
	v_mul_f32_e32 v91, v91, v91
	v_cvt_pk_bf16_f32 v88, v92, v88
	v_max_f32_e32 v80, 0, v80
	v_max_f32_e32 v81, 0, v81
	v_cvt_pk_bf16_f32 v89, v89, v90
	v_cvt_pk_bf16_f32 v90, v97, v93
	v_cvt_pk_bf16_f32 v91, v94, v91
	global_store_dwordx4 v96, v[88:91], s[20:21]
	s_nop 0
	v_max_f32_e32 v82, 0, v82
	v_mul_f32_e32 v88, v80, v80
	v_max_f32_e32 v80, v85, v85
	v_mul_f32_e32 v85, v81, v81
	v_max_f32_e32 v80, 0, v80
	v_max_f32_e32 v81, 0, v86
	v_mul_f32_e32 v86, v82, v82
	v_max_f32_e32 v84, 0, v84
	v_mul_f32_e32 v80, v80, v80
	v_mul_f32_e32 v81, v81, v81
	v_max_f32_e32 v82, 0, v87
	v_max_f32_e32 v83, 0, v83
	s_or_b32 s24, s24, 48
	v_mul_f32_e32 v84, v84, v84
	v_mul_f32_e32 v82, v82, v82
	v_mul_f32_e32 v83, v83, v83
	v_cvt_pk_bf16_f32 v80, v84, v80
	v_cvt_pk_bf16_f32 v81, v81, v82
	s_lshr_b32 s24, s24, 3
	v_max_f32_e32 v72, 0, v72
	v_cvt_pk_bf16_f32 v82, v88, v85
	v_cvt_pk_bf16_f32 v83, v86, v83
	global_store_dwordx4 v96, v[80:83], s[22:23]
	s_and_b32 s24, s24, 14
	v_max_f32_e32 v73, 0, v73
	v_mul_f32_e32 v81, v72, v72
	v_max_f32_e32 v74, 0, v74
	s_or_b32 s24, s24, s45
	v_max_f32_e32 v72, 0, v77
	v_mul_f32_e32 v77, v73, v73
	v_max_f32_e32 v73, v78, v78
	v_mul_f32_e32 v78, v74, v74
	s_lshl_b32 s24, s24, 10
	v_max_f32_e32 v76, 0, v76
	v_mul_f32_e32 v72, v72, v72
	v_max_f32_e32 v73, 0, v73
	v_max_f32_e32 v74, 0, v79
	v_max_f32_e32 v75, 0, v75
	v_bitop3_b32 v80, v137, s24, v138 bitop3:0xde
	v_mul_f32_e32 v76, v76, v76
	v_mul_f32_e32 v73, v73, v73
	v_mul_f32_e32 v74, v74, v74
	v_mul_f32_e32 v75, v75, v75
	v_cvt_pk_bf16_f32 v72, v76, v72
	v_max_f32_e32 v64, 0, v64
	v_cvt_pk_bf16_f32 v73, v73, v74
	v_cvt_pk_bf16_f32 v74, v81, v77
	v_cvt_pk_bf16_f32 v75, v78, v75
	global_store_dwordx4 v80, v[72:75], s[20:21]
	v_max_f32_e32 v65, 0, v65
	v_max_f32_e32 v66, 0, v66
	v_mul_f32_e32 v72, v64, v64
	v_max_f32_e32 v64, 0, v69
	v_mul_f32_e32 v69, v65, v65
	v_max_f32_e32 v65, v70, v70
	v_mul_f32_e32 v70, v66, v66
	v_max_f32_e32 v68, 0, v68
	v_mul_f32_e32 v64, v64, v64
	v_max_f32_e32 v65, 0, v65
	v_max_f32_e32 v66, 0, v71
	v_max_f32_e32 v67, 0, v67
	v_mul_f32_e32 v68, v68, v68
	v_mul_f32_e32 v65, v65, v65
	v_mul_f32_e32 v66, v66, v66
	v_mul_f32_e32 v67, v67, v67
	v_cvt_pk_bf16_f32 v64, v68, v64
	v_cvt_pk_bf16_f32 v65, v65, v66
	v_cvt_pk_bf16_f32 v66, v72, v69
	v_cvt_pk_bf16_f32 v67, v70, v67
	global_store_dwordx4 v80, v[64:67], s[22:23]
	s_nop 0
	v_max_f32_e32 v56, 0, v56
	v_add_u32_e32 v64, 0x80, v136
	v_and_b32_e32 v65, 0xffffff80, v64
	v_lshlrev_b32_e32 v66, 6, v64
	v_lshlrev_b32_e32 v64, 2, v64
	v_and_or_b32 v66, v66, s28, v133
	v_and_b32_e32 v64, 32, v64
	v_bitop3_b32 v152, v66, s46, v64 bitop3:0xde
	v_mul_f32_e32 v64, v56, v56
	v_max_f32_e32 v57, 0, v57
	v_max_f32_e32 v58, 0, v58
	v_max_f32_e32 v60, 0, v60
	v_max_f32_e32 v56, 0, v61
	v_mul_f32_e32 v61, v57, v57
	v_max_f32_e32 v57, v62, v62
	v_mul_f32_e32 v62, v58, v58
	v_mul_f32_e32 v60, v60, v60
	v_mul_f32_e32 v56, v56, v56
	v_max_f32_e32 v57, 0, v57
	v_max_f32_e32 v58, 0, v63
	v_mul_f32_e32 v57, v57, v57
	v_mul_f32_e32 v58, v58, v58
	v_cvt_pk_bf16_f32 v56, v60, v56
	v_add_u32_e32 v60, s5, v65
	v_cvt_pk_bf16_f32 v57, v57, v58
	v_cvt_pk_bf16_f32 v58, v64, v61
	v_ashrrev_i32_e32 v61, 31, v60
	v_max_f32_e32 v59, 0, v59
	v_lshlrev_b64 v[60:61], 14, v[60:61]
	v_mul_f32_e32 v59, v59, v59
	v_lshl_add_u64 v[60:61], s[26:27], 0, v[60:61]
	v_cvt_pk_bf16_f32 v59, v62, v59
	v_lshl_add_u64 v[62:63], v[60:61], 0, v[152:153]
	v_max_f32_e32 v48, 0, v48
	global_store_dwordx4 v[62:63], v[56:59], off
	s_nop 0
	v_max_f32_e32 v49, 0, v49
	v_mul_f32_e32 v56, v48, v48
	v_max_f32_e32 v50, 0, v50
	v_max_f32_e32 v52, 0, v52
	v_max_f32_e32 v48, 0, v53
	v_mul_f32_e32 v53, v49, v49
	v_max_f32_e32 v49, v54, v54
	v_mul_f32_e32 v54, v50, v50
	v_mul_f32_e32 v52, v52, v52
	v_mul_f32_e32 v48, v48, v48
	v_max_f32_e32 v49, 0, v49
	v_max_f32_e32 v50, 0, v55
	v_mul_f32_e32 v49, v49, v49
	v_mul_f32_e32 v50, v50, v50
	v_cvt_pk_bf16_f32 v48, v52, v48
	v_add_u32_e32 v52, s15, v65
	v_cvt_pk_bf16_f32 v49, v49, v50
	v_cvt_pk_bf16_f32 v50, v56, v53
	v_ashrrev_i32_e32 v53, 31, v52
	v_max_f32_e32 v51, 0, v51
	v_lshlrev_b64 v[52:53], 14, v[52:53]
	v_mul_f32_e32 v51, v51, v51
; __device__ __forceinline__ unsigned cvt_pk_bf16(float lo, float hi) { unsigned r; asm volatile("v_cvt_pk_bf16_f32 %0, %1, %2" : "=v"(r) : "v"(lo), "v"(hi)); return r; }
; #define PG8_WAIT_V(n) asm volatile("s_waitcnt vmcnt(" #n ")" ::: "memory")
; #define PG8_BAR __builtin_amdgcn_s_barrier()
; template <class Epi>
; __device__ __forceinline__ void gemm_phase(LAS unsigned char* lds, const Gemm g, const StaticOrder& S, const Epi& E) {
;     ...
;         E(acc, cur, wr, wc, fr, fq);
;         if (!has_next) break;
; #pragma unroll
;         for (int a = 0; a < 2; ++a)
; #pragma unroll
;             for (int b = 0; b < 2; ++b)
; #pragma unroll
;                 for (int m = 0; m < 4; ++m)
; #pragma unroll
;                     for (int n = 0; n < 2; ++n) acc[a][b][m][n] = (f32x4){0.f, 0.f, 0.f, 0.f};
;         cur = nxt; cA = nA; cB = nB; ++ui;
;     }
;     PG8_WAIT_V(0);
;     if (wr == 0) PG8_BAR;
;     PG8_BAR;
;     __device__ __forceinline__ void operator()(const f32x4 (&acc)[2][2][4][2], const Unit& u, int wr, int wc, int fr, int fq) const {
;     ...
;             for (int m = 0; m < 4; ++m) {
;                 const int rowi = row0 + ai * HALF + m * 16;
; #pragma unroll
;                 for (int bj = 0; bj < 2; ++bj) {
;                     f32x4 v0 = acc[ai][bj][m][0], v1 = acc[ai][bj][m][1];
; #pragma unroll
;                     for (int j = 0; j < 4; ++j) { const float a = fmaxf(v0[j], 0.f), b = fmaxf(v1[j], 0.f); v0[j] = a * a; v1[j] = b * b; }
;                     u32x4 w; w.x = cvt_pk_bf16(v0[0], v0[1]); w.y = cvt_pk_bf16(v0[2], v0[3]); w.z = cvt_pk_bf16(v1[0], v1[1]); w.w = cvt_pk_bf16(v1[2], v1[3]);
;                     *(u32x4*)(O + tiled_off(rowi, col0 + bj * HALF, DFF / 64)) = w;
	v_lshl_add_u64 v[52:53], s[26:27], 0, v[52:53]
	v_cvt_pk_bf16_f32 v51, v54, v51
	v_lshl_add_u64 v[54:55], v[52:53], 0, v[152:153]
	global_store_dwordx4 v[54:55], v[48:51], off
	s_nop 1
	v_add_u32_e32 v48, 0x90, v136
	v_lshrrev_b32_e32 v49, 3, v48
	v_and_or_b32 v49, v49, 10, s45
	v_lshlrev_b32_e32 v50, 6, v48
	v_lshlrev_b32_e32 v48, 2, v48
	v_and_or_b32 v50, v50, s28, v133
	v_lshlrev_b32_e32 v49, 10, v49
	v_and_b32_e32 v48, 32, v48
	v_max_f32_e32 v40, 0, v40
	v_max_f32_e32 v41, 0, v41
	v_max_f32_e32 v42, 0, v42
	v_bitop3_b32 v152, v50, v49, v48 bitop3:0xde
	v_mul_f32_e32 v48, v40, v40
	v_max_f32_e32 v40, v45, v45
	v_mul_f32_e32 v45, v41, v41
	v_max_f32_e32 v41, v46, v46
	v_mul_f32_e32 v46, v42, v42
	v_max_f32_e32 v44, 0, v44
	v_max_f32_e32 v40, 0, v40
	v_max_f32_e32 v41, 0, v41
	v_max_f32_e32 v42, 0, v47
	v_mul_f32_e32 v44, v44, v44
	v_mul_f32_e32 v40, v40, v40
	v_mul_f32_e32 v41, v41, v41
	v_max_f32_e32 v43, 0, v43
	v_mul_f32_e32 v42, v42, v42
	v_mul_f32_e32 v43, v43, v43
	v_cvt_pk_bf16_f32 v40, v44, v40
	v_cvt_pk_bf16_f32 v41, v41, v42
	v_cvt_pk_bf16_f32 v42, v48, v45
	v_lshl_add_u64 v[44:45], v[60:61], 0, v[152:153]
	v_max_f32_e32 v32, 0, v32
	v_max_f32_e32 v33, 0, v33
	v_max_f32_e32 v34, 0, v34
	v_cvt_pk_bf16_f32 v43, v46, v43
	global_store_dwordx4 v[44:45], v[40:43], off
	s_nop 0
	v_max_f32_e32 v36, 0, v36
	v_mul_f32_e32 v40, v32, v32
	v_max_f32_e32 v32, v37, v37
	v_mul_f32_e32 v37, v33, v33
	v_max_f32_e32 v33, v38, v38
	v_mul_f32_e32 v38, v34, v34
	v_max_f32_e32 v32, 0, v32
	v_max_f32_e32 v33, 0, v33
	v_max_f32_e32 v34, 0, v39
	v_mul_f32_e32 v36, v36, v36
	v_mul_f32_e32 v32, v32, v32
	v_mul_f32_e32 v33, v33, v33
	v_max_f32_e32 v35, 0, v35
	v_mul_f32_e32 v34, v34, v34
	v_mul_f32_e32 v35, v35, v35
	v_cvt_pk_bf16_f32 v32, v36, v32
	v_cvt_pk_bf16_f32 v33, v33, v34
	v_cvt_pk_bf16_f32 v34, v40, v37
	v_lshl_add_u64 v[36:37], v[52:53], 0, v[152:153]
	v_cvt_pk_bf16_f32 v35, v38, v35
	global_store_dwordx4 v[36:37], v[32:35], off
	s_nop 1
	v_add_u32_e32 v32, 0xa0, v136
	v_lshrrev_b32_e32 v33, 3, v32
	v_and_or_b32 v33, v33, 12, s45
	v_lshlrev_b32_e32 v34, 6, v32
	v_lshlrev_b32_e32 v32, 2, v32
	v_and_or_b32 v34, v34, s28, v133
	v_lshlrev_b32_e32 v33, 10, v33
	v_and_b32_e32 v32, 32, v32
	v_max_f32_e32 v24, 0, v24
	v_max_f32_e32 v25, 0, v25
	v_max_f32_e32 v26, 0, v26
	v_bitop3_b32 v152, v34, v33, v32 bitop3:0xde
	v_mul_f32_e32 v32, v24, v24
	v_max_f32_e32 v24, v29, v29
	v_mul_f32_e32 v29, v25, v25
	v_max_f32_e32 v25, v30, v30
	v_mul_f32_e32 v30, v26, v26
	v_max_f32_e32 v28, 0, v28
	v_max_f32_e32 v24, 0, v24
	v_max_f32_e32 v25, 0, v25
	v_max_f32_e32 v26, 0, v31
	v_mul_f32_e32 v28, v28, v28
	v_mul_f32_e32 v24, v24, v24
	v_mul_f32_e32 v25, v25, v25
	v_max_f32_e32 v27, 0, v27
	v_mul_f32_e32 v26, v26, v26
	v_mul_f32_e32 v27, v27, v27
	v_cvt_pk_bf16_f32 v24, v28, v24
	v_cvt_pk_bf16_f32 v25, v25, v26
	v_cvt_pk_bf16_f32 v26, v32, v29
	v_lshl_add_u64 v[28:29], v[60:61], 0, v[152:153]
	v_max_f32_e32 v16, 0, v16
	v_max_f32_e32 v17, 0, v17
	v_max_f32_e32 v18, 0, v18
	v_cvt_pk_bf16_f32 v27, v30, v27
	global_store_dwordx4 v[28:29], v[24:27], off
	s_nop 0
	v_max_f32_e32 v20, 0, v20
	v_mul_f32_e32 v24, v16, v16
	v_max_f32_e32 v16, v21, v21
	v_mul_f32_e32 v21, v17, v17
	v_max_f32_e32 v17, v22, v22
	v_mul_f32_e32 v22, v18, v18
	v_max_f32_e32 v16, 0, v16
	v_max_f32_e32 v17, 0, v17
	v_max_f32_e32 v18, 0, v23
	v_mul_f32_e32 v20, v20, v20
	v_mul_f32_e32 v16, v16, v16
	v_mul_f32_e32 v17, v17, v17
	v_max_f32_e32 v19, 0, v19
	v_mul_f32_e32 v18, v18, v18
	v_mul_f32_e32 v19, v19, v19
	v_cvt_pk_bf16_f32 v16, v20, v16
	v_cvt_pk_bf16_f32 v17, v17, v18
	v_cvt_pk_bf16_f32 v18, v24, v21
	v_lshl_add_u64 v[20:21], v[52:53], 0, v[152:153]
	v_cvt_pk_bf16_f32 v19, v22, v19
	global_store_dwordx4 v[20:21], v[16:19], off
	s_nop 1
	v_add_u32_e32 v16, 0xb0, v136
	v_lshrrev_b32_e32 v17, 3, v16
	v_and_or_b32 v17, v17, 14, s45
	v_lshlrev_b32_e32 v18, 6, v16
	v_lshlrev_b32_e32 v16, 2, v16
	v_and_or_b32 v18, v18, s28, v133
	v_lshlrev_b32_e32 v17, 10, v17
	v_and_b32_e32 v16, 32, v16
	v_max_f32_e32 v8, 0, v8
	v_max_f32_e32 v9, 0, v9
	v_max_f32_e32 v10, 0, v10
	v_bitop3_b32 v152, v18, v17, v16 bitop3:0xde
	v_mul_f32_e32 v16, v8, v8
	v_max_f32_e32 v8, v13, v13
	v_mul_f32_e32 v13, v9, v9
	v_max_f32_e32 v9, v14, v14
	v_mul_f32_e32 v14, v10, v10
	v_max_f32_e32 v12, 0, v12
	v_max_f32_e32 v8, 0, v8
	v_max_f32_e32 v9, 0, v9
	v_max_f32_e32 v10, 0, v15
	v_mul_f32_e32 v12, v12, v12
	v_mul_f32_e32 v8, v8, v8
	v_mul_f32_e32 v9, v9, v9
	v_max_f32_e32 v11, 0, v11
	v_mul_f32_e32 v10, v10, v10
	v_mul_f32_e32 v11, v11, v11
	v_cvt_pk_bf16_f32 v8, v12, v8
	v_cvt_pk_bf16_f32 v9, v9, v10
	v_cvt_pk_bf16_f32 v10, v16, v13
	v_lshl_add_u64 v[12:13], v[60:61], 0, v[152:153]
	v_max_f32_e32 v0, 0, v0
	v_max_f32_e32 v1, 0, v1
	v_max_f32_e32 v2, 0, v2
	v_cvt_pk_bf16_f32 v11, v14, v11
	global_store_dwordx4 v[12:13], v[8:11], off
	s_nop 0
	v_max_f32_e32 v4, 0, v4
	v_mul_f32_e32 v8, v0, v0
	v_max_f32_e32 v0, v5, v5
	v_mul_f32_e32 v5, v1, v1
	v_max_f32_e32 v1, v6, v6
	v_mul_f32_e32 v6, v2, v2
	v_max_f32_e32 v0, 0, v0
	v_max_f32_e32 v1, 0, v1
	v_max_f32_e32 v2, 0, v7
	v_mul_f32_e32 v4, v4, v4
	v_mul_f32_e32 v0, v0, v0
	v_mul_f32_e32 v1, v1, v1
	v_max_f32_e32 v3, 0, v3
	v_mul_f32_e32 v2, v2, v2
	s_mov_b32 s54, 0xd00ab22c
	v_mul_f32_e32 v3, v3, v3
	v_cvt_pk_bf16_f32 v0, v4, v0
	v_cvt_pk_bf16_f32 v1, v1, v2
	v_cvt_pk_bf16_f32 v2, v8, v5
	v_lshl_add_u64 v[4:5], v[52:53], 0, v[152:153]
	s_and_b64 vcc, exec, s[0:1]
	s_mov_b32 s21, s4
	s_mov_b32 s20, s14
	s_mov_b64 s[24:25], s[18:19]
	s_mov_b64 s[22:23], s[16:17]
	s_mov_b32 s55, 0x3febb5fa
	v_cvt_pk_bf16_f32 v3, v6, v3
	global_store_dwordx4 v[4:5], v[0:3], off
	s_cbranch_vccz .LBB0_134
	s_waitcnt vmcnt(0)
	s_cmpk_gt_u32 s31, 0xff
	s_cbranch_scc1 .LBB0_145
	s_barrier

; #define PG8_STAGE(bufoff, gbase, voff) do { _Pragma("unroll") for (int _i = 0; _i < 2; ++_i) \
;         __builtin_amdgcn_global_load_lds((const unsigned*)((const char*)(gbase) + (voff)[_i]), (LAS unsigned*)(lds + (bufoff) + ldsw + _i * 8192), 16, 0, 0); } while (0)
; #define PG8_LDA(dst, b, h) do { _Pragma("unroll") for (int m = 0; m < 4; ++m) _Pragma("unroll") for (int k = 0; k < 2; ++k) dst[m][k] = *(const LAS bf16x8*)(lds + PG8_SA(b, h) + aoff + m * 2048 + k * 1024); } while (0)
; #define PG8_LDB(dst, b, h) do { _Pragma("unroll") for (int n = 0; n < 2; ++n) _Pragma("unroll") for (int k = 0; k < 2; ++k) dst[n][k] = *(const LAS bf16x8*)(lds + PG8_SB(b, h) + boff + n * 2048 + k * 1024); } while (0)
; #define PG8_MMA(ai, bj, At, Bt) do { __builtin_amdgcn_s_setprio(1); _Pragma("unroll") for (int m = 0; m < 4; ++m) _Pragma("unroll") for (int n = 0; n < 2; ++n) _Pragma("unroll") for (int k = 0; k < 2; ++k) \
;         acc[ai][bj][m][n] = __builtin_amdgcn_mfma_f32_16x16x32_bf16(Bt[n][k], At[m][k], acc[ai][bj][m][n], 0, 0, 0); __builtin_amdgcn_s_setprio(0); } while (0)
; #define PG8_WAIT_L(n) asm volatile("s_waitcnt lgkmcnt(" #n ")" ::: "memory")
; #define PG8_BAR __builtin_amdgcn_s_barrier()
; #define PG8_SCHED __builtin_amdgcn_sched_barrier(0)
; template <class Epi>
; __device__ __forceinline__ void gemm_phase(LAS unsigned char* lds, const Gemm g, const StaticOrder& S, const Epi& E) {
;     ...
;             const bool last = (t == nt - 2);
;             const char* a1 = cA + (size_t)(t + 1) * kstep;
;             const char* a2 = last ? nA : cA + (size_t)(t + 2) * kstep; const char* b2 = last ? nB : cB + (size_t)(t + 2) * kstep;
;             const char* a3 = a2 + kstep; const char* b3 = b2 + kstep;
;             PG8_LDB(B0, 0, 0); PG8_SCHED; PG8_LDA(At, 0, 0); PG8_STAGE(PG8_SA(1, 1), a1 + hstepA, voffA);
;             PG8_WAIT_L(8); PG8_BAR; PG8_WAIT_L(0); PG8_MMA(0, 0, At, B0); PG8_BAR; PG8_SCHED;
;             PG8_LDB(B1, 0, 1); PG8_STAGE(PG8_SB(0, 0), b2, voffB);
;             PG8_BAR; PG8_WAIT_L(0); PG8_MMA(0, 1, At, B1); PG8_BAR;
;             PG8_LDA(At, 0, 1); PG8_STAGE(PG8_SA(0, 0), a2, voffA);
;             PG8_BAR; PG8_WAIT_L(0); PG8_MMA(1, 0, At, B0); PG8_BAR; PG8_SCHED;
.LBB0_187:
	s_add_i32 s54, s22, 2
	s_add_u32 s23, s4, 0x4000
	s_addc_u32 s24, s5, 0
	s_cmp_eq_u32 s40, s22
	s_cselect_b32 s26, s6, s23
	s_cselect_b32 s27, s7, s24
	s_cselect_b32 s24, s20, s50
	s_cselect_b32 s25, s21, s51
	s_add_u32 s22, s26, 0x4000
	s_addc_u32 s23, s27, 0
	s_add_i32 s55, 0, 0x10000
	v_add_u32_e32 v140, s55, v207
	ds_read_b128 v[128:131], v140
	ds_read_b128 v[132:135], v140 offset:1024
	ds_read_b128 v[136:139], v140 offset:2048
	ds_read_b128 v[140:143], v140 offset:3072
	v_lshl_add_u64 v[186:187], s[4:5], 0, v[158:159]
	s_add_i32 m0, s33, 0xc000
	ds_read_b128 v[144:147], v209
	ds_read_b128 v[148:151], v209 offset:1024
	ds_read_b128 v[162:165], v209 offset:2048
	ds_read_b128 v[166:169], v209 offset:3072
	ds_read_b128 v[170:173], v209 offset:4096
	ds_read_b128 v[174:177], v209 offset:5120
	ds_read_b128 v[178:181], v209 offset:6144
	ds_read_b128 v[182:185], v209 offset:7168
	global_load_lds_dwordx4 v[186:187], off
	s_add_i32 m0, s33, 0xe000
	v_lshl_add_u64 v[186:187], s[4:5], 0, v[160:161]
	global_load_lds_dwordx4 v[186:187], off
	s_waitcnt lgkmcnt(8)
	s_barrier
	s_waitcnt lgkmcnt(0)
	v_mfma_f32_16x16x32_bf16 v[124:127], v[128:131], v[144:147], v[124:127]
	s_setprio 1
	v_mfma_f32_16x16x32_bf16 v[120:123], v[136:139], v[144:147], v[120:123]
	v_mfma_f32_16x16x32_bf16 v[116:119], v[128:131], v[162:165], v[116:119]
	v_mfma_f32_16x16x32_bf16 v[112:115], v[136:139], v[162:165], v[112:115]
	v_mfma_f32_16x16x32_bf16 v[108:111], v[128:131], v[170:173], v[108:111]
	v_mfma_f32_16x16x32_bf16 v[104:107], v[136:139], v[170:173], v[104:107]
	v_mfma_f32_16x16x32_bf16 v[100:103], v[128:131], v[178:181], v[100:103]
	v_mfma_f32_16x16x32_bf16 v[96:99], v[136:139], v[178:181], v[96:99]
	v_mfma_f32_16x16x32_bf16 v[124:127], v[132:135], v[148:151], v[124:127]
	v_mfma_f32_16x16x32_bf16 v[120:123], v[140:143], v[148:151], v[120:123]
	v_mfma_f32_16x16x32_bf16 v[116:119], v[132:135], v[166:169], v[116:119]
	v_mfma_f32_16x16x32_bf16 v[112:115], v[140:143], v[166:169], v[112:115]
	v_mfma_f32_16x16x32_bf16 v[108:111], v[132:135], v[174:177], v[108:111]
	v_mfma_f32_16x16x32_bf16 v[104:107], v[140:143], v[174:177], v[104:107]
	v_mfma_f32_16x16x32_bf16 v[100:103], v[132:135], v[182:185], v[100:103]
	s_setprio 0
	v_mfma_f32_16x16x32_bf16 v[96:99], v[140:143], v[182:185], v[96:99]
	s_barrier
	s_add_i32 s58, 0, 0x14000
	s_add_i32 s55, s55, s31
	v_add_u32_e32 v198, s58, v207
	v_lshl_add_u64 v[202:203], s[24:25], 0, v[152:153]
	s_mov_b32 m0, s55
	ds_read_b128 v[186:189], v198
	ds_read_b128 v[190:193], v198 offset:1024
	ds_read_b128 v[194:197], v198 offset:2048
	ds_read_b128 v[198:201], v198 offset:3072
	global_load_lds_dwordx4 v[202:203], off
	s_add_i32 m0, s55, 0x2000
	v_lshl_add_u64 v[202:203], s[24:25], 0, v[156:157]
	global_load_lds_dwordx4 v[202:203], off
	s_barrier
	s_waitcnt lgkmcnt(0)
	v_mfma_f32_16x16x32_bf16 v[92:95], v[186:189], v[144:147], v[92:95]
	s_setprio 1
	v_mfma_f32_16x16x32_bf16 v[88:91], v[194:197], v[144:147], v[88:91]
	s_mov_b32 m0, s33
	v_lshl_add_u64 v[202:203], s[26:27], 0, v[152:153]
	v_mfma_f32_16x16x32_bf16 v[84:87], v[186:189], v[162:165], v[84:87]
	v_mfma_f32_16x16x32_bf16 v[80:83], v[194:197], v[162:165], v[80:83]
	v_mfma_f32_16x16x32_bf16 v[76:79], v[186:189], v[170:173], v[76:79]
	v_mfma_f32_16x16x32_bf16 v[72:75], v[194:197], v[170:173], v[72:75]
	v_mfma_f32_16x16x32_bf16 v[68:71], v[186:189], v[178:181], v[68:71]
	v_mfma_f32_16x16x32_bf16 v[64:67], v[194:197], v[178:181], v[64:67]
	v_mfma_f32_16x16x32_bf16 v[92:95], v[190:193], v[148:151], v[92:95]
	v_mfma_f32_16x16x32_bf16 v[88:91], v[198:201], v[148:151], v[88:91]
	v_mfma_f32_16x16x32_bf16 v[84:87], v[190:193], v[166:169], v[84:87]
	v_mfma_f32_16x16x32_bf16 v[80:83], v[198:201], v[166:169], v[80:83]
	v_mfma_f32_16x16x32_bf16 v[76:79], v[190:193], v[174:177], v[76:79]
	v_mfma_f32_16x16x32_bf16 v[72:75], v[198:201], v[174:177], v[72:75]
	v_mfma_f32_16x16x32_bf16 v[68:71], v[190:193], v[182:185], v[68:71]
	s_setprio 0
	v_mfma_f32_16x16x32_bf16 v[64:67], v[198:201], v[182:185], v[64:67]
	s_barrier
	ds_read_b128 v[144:147], v209 offset:16384
	ds_read_b128 v[148:151], v209 offset:17408
	ds_read_b128 v[162:165], v209 offset:18432
	ds_read_b128 v[166:169], v209 offset:19456
	ds_read_b128 v[170:173], v209 offset:20480
	ds_read_b128 v[174:177], v209 offset:21504
	ds_read_b128 v[178:181], v209 offset:22528
	ds_read_b128 v[182:185], v209 offset:23552
	global_load_lds_dwordx4 v[202:203], off
	s_mov_b32 m0, s34
	v_lshl_add_u64 v[202:203], s[26:27], 0, v[156:157]
	global_load_lds_dwordx4 v[202:203], off
	s_barrier
	s_waitcnt lgkmcnt(0)
	v_mfma_f32_16x16x32_bf16 v[60:63], v[128:131], v[144:147], v[60:63]
	s_setprio 1
	v_mfma_f32_16x16x32_bf16 v[56:59], v[136:139], v[144:147], v[56:59]
	v_mfma_f32_16x16x32_bf16 v[52:55], v[128:131], v[162:165], v[52:55]
	v_mfma_f32_16x16x32_bf16 v[48:51], v[136:139], v[162:165], v[48:51]
	v_mfma_f32_16x16x32_bf16 v[44:47], v[128:131], v[170:173], v[44:47]
	v_mfma_f32_16x16x32_bf16 v[40:43], v[136:139], v[170:173], v[40:43]
	v_mfma_f32_16x16x32_bf16 v[36:39], v[128:131], v[178:181], v[36:39]
	v_mfma_f32_16x16x32_bf16 v[32:35], v[136:139], v[178:181], v[32:35]
	v_mfma_f32_16x16x32_bf16 v[60:63], v[132:135], v[148:151], v[60:63]
	v_mfma_f32_16x16x32_bf16 v[56:59], v[140:143], v[148:151], v[56:59]
	v_mfma_f32_16x16x32_bf16 v[52:55], v[132:135], v[166:169], v[52:55]
	v_mfma_f32_16x16x32_bf16 v[48:51], v[140:143], v[166:169], v[48:51]
	v_mfma_f32_16x16x32_bf16 v[44:47], v[132:135], v[174:177], v[44:47]
	v_mfma_f32_16x16x32_bf16 v[40:43], v[140:143], v[174:177], v[40:43]
	v_mfma_f32_16x16x32_bf16 v[36:39], v[132:135], v[182:185], v[36:39]
	s_setprio 0
	v_mfma_f32_16x16x32_bf16 v[32:35], v[140:143], v[182:185], v[32:35]
	s_barrier
; #define PG8_STAGE(bufoff, gbase, voff) do { _Pragma("unroll") for (int _i = 0; _i < 2; ++_i) \
;         __builtin_amdgcn_global_load_lds((const unsigned*)((const char*)(gbase) + (voff)[_i]), (LAS unsigned*)(lds + (bufoff) + ldsw + _i * 8192), 16, 0, 0); } while (0)
; #define PG8_LDA(dst, b, h) do { _Pragma("unroll") for (int m = 0; m < 4; ++m) _Pragma("unroll") for (int k = 0; k < 2; ++k) dst[m][k] = *(const LAS bf16x8*)(lds + PG8_SA(b, h) + aoff + m * 2048 + k * 1024); } while (0)
; #define PG8_LDB(dst, b, h) do { _Pragma("unroll") for (int n = 0; n < 2; ++n) _Pragma("unroll") for (int k = 0; k < 2; ++k) dst[n][k] = *(const LAS bf16x8*)(lds + PG8_SB(b, h) + boff + n * 2048 + k * 1024); } while (0)
; #define PG8_MMA(ai, bj, At, Bt) do { __builtin_amdgcn_s_setprio(1); _Pragma("unroll") for (int m = 0; m < 4; ++m) _Pragma("unroll") for (int n = 0; n < 2; ++n) _Pragma("unroll") for (int k = 0; k < 2; ++k) \
;         acc[ai][bj][m][n] = __builtin_amdgcn_mfma_f32_16x16x32_bf16(Bt[n][k], At[m][k], acc[ai][bj][m][n], 0, 0, 0); __builtin_amdgcn_s_setprio(0); } while (0)
; #define PG8_WAIT_V(n) asm volatile("s_waitcnt vmcnt(" #n ")" ::: "memory")
; #define PG8_WAIT_L(n) asm volatile("s_waitcnt lgkmcnt(" #n ")" ::: "memory")
; #define PG8_BAR __builtin_amdgcn_s_barrier()
; #define PG8_SCHED __builtin_amdgcn_sched_barrier(0)
; template <class Epi>
; __device__ __forceinline__ void gemm_phase(LAS unsigned char* lds, const Gemm g, const StaticOrder& S, const Epi& E) {
;     ...
;             PG8_STAGE(PG8_SB(0, 1), b2 + hstepB, voffB);
;             PG8_WAIT_V(6); PG8_BAR; PG8_MMA(1, 1, At, B1); PG8_BAR;
;             PG8_LDB(B0, 1, 0); PG8_SCHED; PG8_LDA(At, 1, 0); PG8_STAGE(PG8_SA(0, 1), a2 + hstepA, voffA);
;             PG8_WAIT_L(8); PG8_BAR; PG8_WAIT_L(0); PG8_MMA(0, 0, At, B0); PG8_BAR; PG8_SCHED;
;             PG8_LDB(B1, 1, 1); PG8_STAGE(PG8_SB(1, 0), b3, voffB);
	s_add_u32 s56, s24, s52
	s_addc_u32 s57, s25, 0
	s_add_i32 s55, s58, s31
	s_mov_b32 m0, s55
	v_lshl_add_u64 v[128:129], s[56:57], 0, v[152:153]
	global_load_lds_dwordx4 v[128:129], off
	s_add_i32 m0, s55, 0x2000
	v_lshl_add_u64 v[128:129], s[56:57], 0, v[156:157]
	global_load_lds_dwordx4 v[128:129], off
	s_waitcnt vmcnt(6)
	s_barrier
	v_mfma_f32_16x16x32_bf16 v[28:31], v[186:189], v[144:147], v[28:31]
	s_setprio 1
	v_mfma_f32_16x16x32_bf16 v[24:27], v[194:197], v[144:147], v[24:27]
	s_add_i32 s55, 0, 0x18000
	v_add_u32_e32 v140, s55, v207
	v_mfma_f32_16x16x32_bf16 v[20:23], v[186:189], v[162:165], v[20:23]
	v_mfma_f32_16x16x32_bf16 v[16:19], v[194:197], v[162:165], v[16:19]
	v_mfma_f32_16x16x32_bf16 v[12:15], v[186:189], v[170:173], v[12:15]
	v_mfma_f32_16x16x32_bf16 v[8:11], v[194:197], v[170:173], v[8:11]
	v_mfma_f32_16x16x32_bf16 v[4:7], v[186:189], v[178:181], v[4:7]
	v_mfma_f32_16x16x32_bf16 v[0:3], v[194:197], v[178:181], v[0:3]
	v_mfma_f32_16x16x32_bf16 v[28:31], v[190:193], v[148:151], v[28:31]
	v_mfma_f32_16x16x32_bf16 v[24:27], v[198:201], v[148:151], v[24:27]
	v_mfma_f32_16x16x32_bf16 v[20:23], v[190:193], v[166:169], v[20:23]
	v_mfma_f32_16x16x32_bf16 v[16:19], v[198:201], v[166:169], v[16:19]
	v_mfma_f32_16x16x32_bf16 v[12:15], v[190:193], v[174:177], v[12:15]
	v_mfma_f32_16x16x32_bf16 v[8:11], v[198:201], v[174:177], v[8:11]
	v_mfma_f32_16x16x32_bf16 v[4:7], v[190:193], v[182:185], v[4:7]
	s_setprio 0
	v_mfma_f32_16x16x32_bf16 v[0:3], v[198:201], v[182:185], v[0:3]
	s_barrier
	ds_read_b128 v[128:131], v140
	ds_read_b128 v[132:135], v140 offset:1024
	ds_read_b128 v[136:139], v140 offset:2048
	ds_read_b128 v[140:143], v140 offset:3072
	s_add_u32 s26, s26, s52
	s_addc_u32 s27, s27, 0
	s_mov_b32 m0, s35
	v_lshl_add_u64 v[186:187], s[26:27], 0, v[152:153]
	ds_read_b128 v[144:147], v209 offset:32768
	ds_read_b128 v[148:151], v209 offset:33792
	ds_read_b128 v[162:165], v209 offset:34816
	ds_read_b128 v[166:169], v209 offset:35840
	ds_read_b128 v[170:173], v209 offset:36864
	ds_read_b128 v[174:177], v209 offset:37888
	ds_read_b128 v[178:181], v209 offset:38912
	ds_read_b128 v[182:185], v209 offset:39936
	global_load_lds_dwordx4 v[186:187], off
	s_mov_b32 m0, s36
	v_lshl_add_u64 v[186:187], s[26:27], 0, v[156:157]
	global_load_lds_dwordx4 v[186:187], off
	s_waitcnt lgkmcnt(8)
	s_barrier
	s_waitcnt lgkmcnt(0)
	v_mfma_f32_16x16x32_bf16 v[124:127], v[128:131], v[144:147], v[124:127]
	s_setprio 1
	v_mfma_f32_16x16x32_bf16 v[120:123], v[136:139], v[144:147], v[120:123]
	v_mfma_f32_16x16x32_bf16 v[116:119], v[128:131], v[162:165], v[116:119]
	v_mfma_f32_16x16x32_bf16 v[112:115], v[136:139], v[162:165], v[112:115]
	v_mfma_f32_16x16x32_bf16 v[108:111], v[128:131], v[170:173], v[108:111]
	v_mfma_f32_16x16x32_bf16 v[104:107], v[136:139], v[170:173], v[104:107]
	v_mfma_f32_16x16x32_bf16 v[100:103], v[128:131], v[178:181], v[100:103]
	v_mfma_f32_16x16x32_bf16 v[96:99], v[136:139], v[178:181], v[96:99]
	v_mfma_f32_16x16x32_bf16 v[124:127], v[132:135], v[148:151], v[124:127]
	v_mfma_f32_16x16x32_bf16 v[120:123], v[140:143], v[148:151], v[120:123]
	v_mfma_f32_16x16x32_bf16 v[116:119], v[132:135], v[166:169], v[116:119]
	v_mfma_f32_16x16x32_bf16 v[112:115], v[140:143], v[166:169], v[112:115]
	v_mfma_f32_16x16x32_bf16 v[108:111], v[132:135], v[174:177], v[108:111]
	v_mfma_f32_16x16x32_bf16 v[104:107], v[140:143], v[174:177], v[104:107]
	v_mfma_f32_16x16x32_bf16 v[100:103], v[132:135], v[182:185], v[100:103]
	s_setprio 0
	v_mfma_f32_16x16x32_bf16 v[96:99], v[140:143], v[182:185], v[96:99]
	s_barrier
	s_add_i32 s26, 0, 0x1c000
	s_add_u32 s24, s24, 0x4000
	s_addc_u32 s25, s25, 0
	s_add_i32 s27, s55, s31
	v_add_u32_e32 v198, s26, v207
	v_lshl_add_u64 v[202:203], s[24:25], 0, v[152:153]
	s_mov_b32 m0, s27
	ds_read_b128 v[186:189], v198
	ds_read_b128 v[190:193], v198 offset:1024
	ds_read_b128 v[194:197], v198 offset:2048
	ds_read_b128 v[198:201], v198 offset:3072
	global_load_lds_dwordx4 v[202:203], off
	s_add_i32 m0, s27, 0x2000
	v_lshl_add_u64 v[202:203], s[24:25], 0, v[156:157]
	global_load_lds_dwordx4 v[202:203], off
	s_barrier
; #define PG8_STAGE(bufoff, gbase, voff) do { _Pragma("unroll") for (int _i = 0; _i < 2; ++_i) \
;         __builtin_amdgcn_global_load_lds((const unsigned*)((const char*)(gbase) + (voff)[_i]), (LAS unsigned*)(lds + (bufoff) + ldsw + _i * 8192), 16, 0, 0); } while (0)
; #define PG8_LDA(dst, b, h) do { _Pragma("unroll") for (int m = 0; m < 4; ++m) _Pragma("unroll") for (int k = 0; k < 2; ++k) dst[m][k] = *(const LAS bf16x8*)(lds + PG8_SA(b, h) + aoff + m * 2048 + k * 1024); } while (0)
; #define PG8_MMA(ai, bj, At, Bt) do { __builtin_amdgcn_s_setprio(1); _Pragma("unroll") for (int m = 0; m < 4; ++m) _Pragma("unroll") for (int n = 0; n < 2; ++n) _Pragma("unroll") for (int k = 0; k < 2; ++k) \
;         acc[ai][bj][m][n] = __builtin_amdgcn_mfma_f32_16x16x32_bf16(Bt[n][k], At[m][k], acc[ai][bj][m][n], 0, 0, 0); __builtin_amdgcn_s_setprio(0); } while (0)
; #define PG8_WAIT_V(n) asm volatile("s_waitcnt vmcnt(" #n ")" ::: "memory")
; #define PG8_WAIT_L(n) asm volatile("s_waitcnt lgkmcnt(" #n ")" ::: "memory")
; #define PG8_BAR __builtin_amdgcn_s_barrier()
; #define PG8_SCHED __builtin_amdgcn_sched_barrier(0)
; template <class Epi>
; __device__ __forceinline__ void gemm_phase(LAS unsigned char* lds, const Gemm g, const StaticOrder& S, const Epi& E) {
;     ...
;             PG8_BAR; PG8_WAIT_L(0); PG8_MMA(0, 1, At, B1); PG8_BAR;
;             PG8_LDA(At, 1, 1); PG8_STAGE(PG8_SA(1, 0), a3, voffA);
;             PG8_BAR; PG8_WAIT_L(0); PG8_MMA(1, 0, At, B0); PG8_BAR; PG8_SCHED;
;             PG8_STAGE(PG8_SB(1, 1), b3 + hstepB, voffB);
;             PG8_WAIT_V(6); PG8_BAR; PG8_MMA(1, 1, At, B1); PG8_BAR;
;     __device__ __forceinline__ void operator()(const f32x4 (&acc)[2][2][4][2], const Unit& u, int wr, int wc, int fr, int fq) const {
;         const int row0 = u.pm * BM + wr * 64 + fr, col0 = u.pn * BM + wc * 32 + 8 * fq;
;         const float* gb = gate + (size_t)(row0 >> 12) * (6 * DM);
;         const bool ln = stats != nullptr;
;         constexpr int GB[4] = {0, 4, 8, 16};
;         f32x2 st[4];
; #pragma unroll
;         for (int grp = 0; grp < 3; ++grp) {
;             u32x4 xv[8]; f32x4 cg[2][2], cl[2][2], cb[2][2];
;             if (grp == 0 || grp == 2) {
; #pragma unroll
;                 for (int m = 0; m < 4; ++m) st[m] = ln ? *(const f32x2*)(stats + 2 * (row0 + (grp ? HALF : 0) + m * 16)) : (f32x2){0.f, 1.f};
	s_waitcnt lgkmcnt(0)
	v_mfma_f32_16x16x32_bf16 v[92:95], v[186:189], v[144:147], v[92:95]
	s_setprio 1
	v_mfma_f32_16x16x32_bf16 v[88:91], v[194:197], v[144:147], v[88:91]
	s_mov_b32 m0, s38
	v_lshl_add_u64 v[202:203], s[22:23], 0, v[152:153]
	v_mfma_f32_16x16x32_bf16 v[84:87], v[186:189], v[162:165], v[84:87]
	v_mfma_f32_16x16x32_bf16 v[80:83], v[194:197], v[162:165], v[80:83]
	v_mfma_f32_16x16x32_bf16 v[76:79], v[186:189], v[170:173], v[76:79]
	v_mfma_f32_16x16x32_bf16 v[72:75], v[194:197], v[170:173], v[72:75]
	v_mfma_f32_16x16x32_bf16 v[68:71], v[186:189], v[178:181], v[68:71]
	v_mfma_f32_16x16x32_bf16 v[64:67], v[194:197], v[178:181], v[64:67]
	v_mfma_f32_16x16x32_bf16 v[92:95], v[190:193], v[148:151], v[92:95]
	v_mfma_f32_16x16x32_bf16 v[88:91], v[198:201], v[148:151], v[88:91]
	v_mfma_f32_16x16x32_bf16 v[84:87], v[190:193], v[166:169], v[84:87]
	v_mfma_f32_16x16x32_bf16 v[80:83], v[198:201], v[166:169], v[80:83]
	v_mfma_f32_16x16x32_bf16 v[76:79], v[190:193], v[174:177], v[76:79]
	v_mfma_f32_16x16x32_bf16 v[72:75], v[198:201], v[174:177], v[72:75]
	v_mfma_f32_16x16x32_bf16 v[68:71], v[190:193], v[182:185], v[68:71]
	s_setprio 0
	v_mfma_f32_16x16x32_bf16 v[64:67], v[198:201], v[182:185], v[64:67]
	s_barrier
	ds_read_b128 v[144:147], v209 offset:49152
	ds_read_b128 v[148:151], v209 offset:50176
	ds_read_b128 v[162:165], v209 offset:51200
	ds_read_b128 v[166:169], v209 offset:52224
	ds_read_b128 v[170:173], v209 offset:53248
	ds_read_b128 v[174:177], v209 offset:54272
	ds_read_b128 v[178:181], v209 offset:55296
	ds_read_b128 v[182:185], v209 offset:56320
	global_load_lds_dwordx4 v[202:203], off
	s_mov_b32 m0, s39
	v_lshl_add_u64 v[202:203], s[22:23], 0, v[156:157]
	global_load_lds_dwordx4 v[202:203], off
	s_barrier
	s_waitcnt lgkmcnt(0)
	v_mfma_f32_16x16x32_bf16 v[60:63], v[128:131], v[144:147], v[60:63]
	s_setprio 1
	v_mfma_f32_16x16x32_bf16 v[56:59], v[136:139], v[144:147], v[56:59]
	v_mfma_f32_16x16x32_bf16 v[52:55], v[128:131], v[162:165], v[52:55]
	v_mfma_f32_16x16x32_bf16 v[48:51], v[136:139], v[162:165], v[48:51]
	v_mfma_f32_16x16x32_bf16 v[44:47], v[128:131], v[170:173], v[44:47]
	v_mfma_f32_16x16x32_bf16 v[40:43], v[136:139], v[170:173], v[40:43]
	v_mfma_f32_16x16x32_bf16 v[36:39], v[128:131], v[178:181], v[36:39]
	v_mfma_f32_16x16x32_bf16 v[32:35], v[136:139], v[178:181], v[32:35]
	v_mfma_f32_16x16x32_bf16 v[60:63], v[132:135], v[148:151], v[60:63]
	v_mfma_f32_16x16x32_bf16 v[56:59], v[140:143], v[148:151], v[56:59]
	v_mfma_f32_16x16x32_bf16 v[52:55], v[132:135], v[166:169], v[52:55]
	v_mfma_f32_16x16x32_bf16 v[48:51], v[140:143], v[166:169], v[48:51]
	v_mfma_f32_16x16x32_bf16 v[44:47], v[132:135], v[174:177], v[44:47]
	v_mfma_f32_16x16x32_bf16 v[40:43], v[140:143], v[174:177], v[40:43]
	v_mfma_f32_16x16x32_bf16 v[36:39], v[132:135], v[182:185], v[36:39]
	s_setprio 0
	v_mfma_f32_16x16x32_bf16 v[32:35], v[140:143], v[182:185], v[32:35]
	s_barrier
	s_add_u32 s22, s24, s52
	s_addc_u32 s23, s25, 0
	s_add_i32 s24, s26, s31
	s_mov_b32 m0, s24
	v_lshl_add_u64 v[128:129], s[22:23], 0, v[152:153]
	global_load_lds_dwordx4 v[128:129], off
	s_add_i32 m0, s24, 0x2000
	v_lshl_add_u64 v[128:129], s[22:23], 0, v[156:157]
	global_load_lds_dwordx4 v[128:129], off
	s_waitcnt vmcnt(6)
	s_barrier
	v_mfma_f32_16x16x32_bf16 v[28:31], v[186:189], v[144:147], v[28:31]
	s_setprio 1
	v_mfma_f32_16x16x32_bf16 v[24:27], v[194:197], v[144:147], v[24:27]
	s_add_u32 s4, s4, 0x8000
	s_addc_u32 s5, s5, 0
	s_add_u32 s50, s50, 0x8000
	s_addc_u32 s51, s51, 0
	v_mfma_f32_16x16x32_bf16 v[20:23], v[186:189], v[162:165], v[20:23]
	v_mfma_f32_16x16x32_bf16 v[16:19], v[194:197], v[162:165], v[16:19]
	v_mfma_f32_16x16x32_bf16 v[12:15], v[186:189], v[170:173], v[12:15]
	v_mfma_f32_16x16x32_bf16 v[8:11], v[194:197], v[170:173], v[8:11]
	v_mfma_f32_16x16x32_bf16 v[4:7], v[186:189], v[178:181], v[4:7]
	v_mfma_f32_16x16x32_bf16 v[0:3], v[194:197], v[178:181], v[0:3]
	v_mfma_f32_16x16x32_bf16 v[28:31], v[190:193], v[148:151], v[28:31]
	v_mfma_f32_16x16x32_bf16 v[24:27], v[198:201], v[148:151], v[24:27]
	v_mfma_f32_16x16x32_bf16 v[20:23], v[190:193], v[166:169], v[20:23]
	v_mfma_f32_16x16x32_bf16 v[16:19], v[198:201], v[166:169], v[16:19]
	v_mfma_f32_16x16x32_bf16 v[12:15], v[190:193], v[174:177], v[12:15]
	v_mfma_f32_16x16x32_bf16 v[8:11], v[198:201], v[174:177], v[8:11]
	v_mfma_f32_16x16x32_bf16 v[4:7], v[190:193], v[182:185], v[4:7]
	s_cmp_ge_u32 s54, s28
	s_mov_b32 s22, s54
	s_setprio 0
	v_mfma_f32_16x16x32_bf16 v[0:3], v[198:201], v[182:185], v[0:3]
	s_barrier
	s_cbranch_scc0 .LBB0_187
	s_lshl_b32 s22, s49, 8
	s_add_i32 s22, s22, s37
	v_or_b32_e32 v162, s22, v206
	v_lshlrev_b32_e32 v170, 1, v162
	v_cndmask_b32_e64 v128, 0, 1, s[12:13]
	v_mov_b32_e32 v182, 1.0
	v_mov_b32_e32 v184, 0
	v_cmp_ne_u32_e64 s[4:5], 1, v128
	s_andn2_b64 vcc, exec, s[12:13]
	v_ashrrev_i32_e32 v171, 31, v170
	v_mov_b32_e32 v192, 0
	v_mov_b32_e32 v194, 1.0
	s_cbranch_vccnz .LBB0_190
	v_lshl_add_u64 v[128:129], v[170:171], 2, s[14:15]
	global_load_dwordx2 v[192:193], v[128:129], off
	s_waitcnt vmcnt(0)
	v_mov_b32_e32 v194, v193

; #define PG8_STAGE(bufoff, gbase, voff) do { _Pragma("unroll") for (int _i = 0; _i < 2; ++_i) \
;         __builtin_amdgcn_global_load_lds((const unsigned*)((const char*)(gbase) + (voff)[_i]), (LAS unsigned*)(lds + (bufoff) + ldsw + _i * 8192), 16, 0, 0); } while (0)
; #define PG8_LDA(dst, b, h) do { _Pragma("unroll") for (int m = 0; m < 4; ++m) _Pragma("unroll") for (int k = 0; k < 2; ++k) dst[m][k] = *(const LAS bf16x8*)(lds + PG8_SA(b, h) + aoff + m * 2048 + k * 1024); } while (0)
; #define PG8_LDB(dst, b, h) do { _Pragma("unroll") for (int n = 0; n < 2; ++n) _Pragma("unroll") for (int k = 0; k < 2; ++k) dst[n][k] = *(const LAS bf16x8*)(lds + PG8_SB(b, h) + boff + n * 2048 + k * 1024); } while (0)
; #define PG8_MMA(ai, bj, At, Bt) do { __builtin_amdgcn_s_setprio(1); _Pragma("unroll") for (int m = 0; m < 4; ++m) _Pragma("unroll") for (int n = 0; n < 2; ++n) _Pragma("unroll") for (int k = 0; k < 2; ++k) \
;         acc[ai][bj][m][n] = __builtin_amdgcn_mfma_f32_16x16x32_bf16(Bt[n][k], At[m][k], acc[ai][bj][m][n], 0, 0, 0); __builtin_amdgcn_s_setprio(0); } while (0)
; #define PG8_WAIT_L(n) asm volatile("s_waitcnt lgkmcnt(" #n ")" ::: "memory")
; #define PG8_BAR __builtin_amdgcn_s_barrier()
; #define PG8_SCHED __builtin_amdgcn_sched_barrier(0)
; template <class Epi>
; __device__ __forceinline__ void gemm_phase(LAS unsigned char* lds, const Gemm g, const StaticOrder& S, const Epi& E) {
;     ...
;             const bool last = (t == nt - 2);
;             const char* a1 = cA + (size_t)(t + 1) * kstep;
;             const char* a2 = last ? nA : cA + (size_t)(t + 2) * kstep; const char* b2 = last ? nB : cB + (size_t)(t + 2) * kstep;
;             const char* a3 = a2 + kstep; const char* b3 = b2 + kstep;
;             PG8_LDB(B0, 0, 0); PG8_SCHED; PG8_LDA(At, 0, 0); PG8_STAGE(PG8_SA(1, 1), a1 + hstepA, voffA);
;             PG8_WAIT_L(8); PG8_BAR; PG8_WAIT_L(0); PG8_MMA(0, 0, At, B0); PG8_BAR; PG8_SCHED;
;             PG8_LDB(B1, 0, 1); PG8_STAGE(PG8_SB(0, 0), b2, voffB);
;             PG8_BAR; PG8_WAIT_L(0); PG8_MMA(0, 1, At, B1); PG8_BAR;
;             PG8_LDA(At, 0, 1); PG8_STAGE(PG8_SA(0, 0), a2, voffA);
;             PG8_BAR; PG8_WAIT_L(0); PG8_MMA(1, 0, At, B0); PG8_BAR; PG8_SCHED;
.LBB0_247:
	s_add_u32 s14, s12, 0xfff84000
	s_addc_u32 s15, s13, -1
	s_cmp_eq_u32 s38, 28
	s_cselect_b32 s18, s11, s14
	s_cselect_b32 s19, s5, s15
	s_cselect_b32 s14, s35, s36
	s_cselect_b32 s15, s3, s37
	s_add_u32 s16, s18, 0x4000
	s_addc_u32 s17, s19, 0
	s_add_i32 s39, 0, 0x10000
	v_add_u32_e32 v140, s39, v170
	ds_read_b128 v[128:131], v140
	ds_read_b128 v[132:135], v140 offset:1024
	ds_read_b128 v[136:139], v140 offset:2048
	ds_read_b128 v[140:143], v140 offset:3072
	v_lshl_add_u64 v[194:195], s[12:13], 0, v[156:157]
	s_add_i32 m0, s25, 0xc000
	ds_read_b128 v[144:147], v172
	ds_read_b128 v[148:151], v172 offset:1024
	ds_read_b128 v[166:169], v172 offset:2048
	ds_read_b128 v[174:177], v172 offset:3072
	ds_read_b128 v[178:181], v172 offset:4096
	ds_read_b128 v[182:185], v172 offset:5120
	ds_read_b128 v[186:189], v172 offset:6144
	ds_read_b128 v[190:193], v172 offset:7168
	global_load_lds_dwordx4 v[194:195], off
	s_add_i32 m0, s25, 0xe000
	v_lshl_add_u64 v[194:195], s[12:13], 0, v[158:159]
	global_load_lds_dwordx4 v[194:195], off
	s_waitcnt lgkmcnt(8)
	s_barrier
	s_waitcnt lgkmcnt(0)
	v_mfma_f32_16x16x32_bf16 v[124:127], v[128:131], v[144:147], v[124:127]
	s_setprio 1
	v_mfma_f32_16x16x32_bf16 v[120:123], v[136:139], v[144:147], v[120:123]
	v_mfma_f32_16x16x32_bf16 v[108:111], v[128:131], v[166:169], v[108:111]
	v_mfma_f32_16x16x32_bf16 v[104:107], v[136:139], v[166:169], v[104:107]
	v_mfma_f32_16x16x32_bf16 v[92:95], v[128:131], v[178:181], v[92:95]
	v_mfma_f32_16x16x32_bf16 v[88:91], v[136:139], v[178:181], v[88:91]
	v_mfma_f32_16x16x32_bf16 v[76:79], v[128:131], v[186:189], v[76:79]
	v_mfma_f32_16x16x32_bf16 v[72:75], v[136:139], v[186:189], v[72:75]
	v_mfma_f32_16x16x32_bf16 v[124:127], v[132:135], v[148:151], v[124:127]
	v_mfma_f32_16x16x32_bf16 v[120:123], v[140:143], v[148:151], v[120:123]
	v_mfma_f32_16x16x32_bf16 v[108:111], v[132:135], v[174:177], v[108:111]
	v_mfma_f32_16x16x32_bf16 v[104:107], v[140:143], v[174:177], v[104:107]
	v_mfma_f32_16x16x32_bf16 v[92:95], v[132:135], v[182:185], v[92:95]
	v_mfma_f32_16x16x32_bf16 v[88:91], v[140:143], v[182:185], v[88:91]
	v_mfma_f32_16x16x32_bf16 v[76:79], v[132:135], v[190:193], v[76:79]
	s_setprio 0
	v_mfma_f32_16x16x32_bf16 v[72:75], v[140:143], v[190:193], v[72:75]
	s_barrier
	s_add_i32 s42, 0, 0x14000
	s_add_i32 s39, s39, s23
	v_add_u32_e32 v152, s42, v170
	v_lshl_add_u64 v[210:211], s[14:15], 0, v[156:157]
	s_mov_b32 m0, s39
	ds_read_b128 v[194:197], v152
	ds_read_b128 v[198:201], v152 offset:1024
	ds_read_b128 v[202:205], v152 offset:2048
	ds_read_b128 v[206:209], v152 offset:3072
	global_load_lds_dwordx4 v[210:211], off
	s_add_i32 m0, s39, 0x2000
	v_lshl_add_u64 v[210:211], s[14:15], 0, v[158:159]
	global_load_lds_dwordx4 v[210:211], off
	s_barrier
	s_waitcnt lgkmcnt(0)
	v_mfma_f32_16x16x32_bf16 v[116:119], v[194:197], v[144:147], v[116:119]
	s_setprio 1
	v_mfma_f32_16x16x32_bf16 v[112:115], v[202:205], v[144:147], v[112:115]
	s_mov_b32 m0, s25
	v_lshl_add_u64 v[210:211], s[18:19], 0, v[156:157]
	v_mfma_f32_16x16x32_bf16 v[100:103], v[194:197], v[166:169], v[100:103]
	v_mfma_f32_16x16x32_bf16 v[96:99], v[202:205], v[166:169], v[96:99]
	v_mfma_f32_16x16x32_bf16 v[84:87], v[194:197], v[178:181], v[84:87]
	v_mfma_f32_16x16x32_bf16 v[80:83], v[202:205], v[178:181], v[80:83]
	v_mfma_f32_16x16x32_bf16 v[68:71], v[194:197], v[186:189], v[68:71]
	v_mfma_f32_16x16x32_bf16 v[64:67], v[202:205], v[186:189], v[64:67]
	v_mfma_f32_16x16x32_bf16 v[116:119], v[198:201], v[148:151], v[116:119]
	v_mfma_f32_16x16x32_bf16 v[112:115], v[206:209], v[148:151], v[112:115]
	v_mfma_f32_16x16x32_bf16 v[100:103], v[198:201], v[174:177], v[100:103]
	v_mfma_f32_16x16x32_bf16 v[96:99], v[206:209], v[174:177], v[96:99]
	v_mfma_f32_16x16x32_bf16 v[84:87], v[198:201], v[182:185], v[84:87]
	v_mfma_f32_16x16x32_bf16 v[80:83], v[206:209], v[182:185], v[80:83]
	v_mfma_f32_16x16x32_bf16 v[68:71], v[198:201], v[190:193], v[68:71]
	s_setprio 0
	v_mfma_f32_16x16x32_bf16 v[64:67], v[206:209], v[190:193], v[64:67]
	s_barrier
	ds_read_b128 v[144:147], v172 offset:16384
	ds_read_b128 v[148:151], v172 offset:17408
	ds_read_b128 v[166:169], v172 offset:18432
	ds_read_b128 v[174:177], v172 offset:19456
	ds_read_b128 v[178:181], v172 offset:20480
	ds_read_b128 v[182:185], v172 offset:21504
	ds_read_b128 v[186:189], v172 offset:22528
	ds_read_b128 v[190:193], v172 offset:23552
	global_load_lds_dwordx4 v[210:211], off
	s_mov_b32 m0, s26
	v_lshl_add_u64 v[210:211], s[18:19], 0, v[158:159]
	global_load_lds_dwordx4 v[210:211], off
	s_barrier
	s_waitcnt lgkmcnt(0)
	v_mfma_f32_16x16x32_bf16 v[60:63], v[128:131], v[144:147], v[60:63]
	s_setprio 1
	v_mfma_f32_16x16x32_bf16 v[56:59], v[136:139], v[144:147], v[56:59]
	v_mfma_f32_16x16x32_bf16 v[44:47], v[128:131], v[166:169], v[44:47]
	v_mfma_f32_16x16x32_bf16 v[40:43], v[136:139], v[166:169], v[40:43]
	v_mfma_f32_16x16x32_bf16 v[28:31], v[128:131], v[178:181], v[28:31]
	v_mfma_f32_16x16x32_bf16 v[24:27], v[136:139], v[178:181], v[24:27]
	v_mfma_f32_16x16x32_bf16 v[12:15], v[128:131], v[186:189], v[12:15]
	v_mfma_f32_16x16x32_bf16 v[8:11], v[136:139], v[186:189], v[8:11]
	v_mfma_f32_16x16x32_bf16 v[60:63], v[132:135], v[148:151], v[60:63]
	v_mfma_f32_16x16x32_bf16 v[56:59], v[140:143], v[148:151], v[56:59]
	v_mfma_f32_16x16x32_bf16 v[44:47], v[132:135], v[174:177], v[44:47]
	v_mfma_f32_16x16x32_bf16 v[40:43], v[140:143], v[174:177], v[40:43]
	v_mfma_f32_16x16x32_bf16 v[28:31], v[132:135], v[182:185], v[28:31]
	v_mfma_f32_16x16x32_bf16 v[24:27], v[140:143], v[182:185], v[24:27]
	v_mfma_f32_16x16x32_bf16 v[12:15], v[132:135], v[190:193], v[12:15]
	s_setprio 0
	v_mfma_f32_16x16x32_bf16 v[8:11], v[140:143], v[190:193], v[8:11]
	s_barrier
; #define PG8_STAGE(bufoff, gbase, voff) do { _Pragma("unroll") for (int _i = 0; _i < 2; ++_i) \
;         __builtin_amdgcn_global_load_lds((const unsigned*)((const char*)(gbase) + (voff)[_i]), (LAS unsigned*)(lds + (bufoff) + ldsw + _i * 8192), 16, 0, 0); } while (0)
; #define PG8_LDA(dst, b, h) do { _Pragma("unroll") for (int m = 0; m < 4; ++m) _Pragma("unroll") for (int k = 0; k < 2; ++k) dst[m][k] = *(const LAS bf16x8*)(lds + PG8_SA(b, h) + aoff + m * 2048 + k * 1024); } while (0)
; #define PG8_LDB(dst, b, h) do { _Pragma("unroll") for (int n = 0; n < 2; ++n) _Pragma("unroll") for (int k = 0; k < 2; ++k) dst[n][k] = *(const LAS bf16x8*)(lds + PG8_SB(b, h) + boff + n * 2048 + k * 1024); } while (0)
; #define PG8_MMA(ai, bj, At, Bt) do { __builtin_amdgcn_s_setprio(1); _Pragma("unroll") for (int m = 0; m < 4; ++m) _Pragma("unroll") for (int n = 0; n < 2; ++n) _Pragma("unroll") for (int k = 0; k < 2; ++k) \
;         acc[ai][bj][m][n] = __builtin_amdgcn_mfma_f32_16x16x32_bf16(Bt[n][k], At[m][k], acc[ai][bj][m][n], 0, 0, 0); __builtin_amdgcn_s_setprio(0); } while (0)
; #define PG8_WAIT_V(n) asm volatile("s_waitcnt vmcnt(" #n ")" ::: "memory")
; #define PG8_WAIT_L(n) asm volatile("s_waitcnt lgkmcnt(" #n ")" ::: "memory")
; #define PG8_BAR __builtin_amdgcn_s_barrier()
; #define PG8_SCHED __builtin_amdgcn_sched_barrier(0)
; template <class Epi>
; __device__ __forceinline__ void gemm_phase(LAS unsigned char* lds, const Gemm g, const StaticOrder& S, const Epi& E) {
;     ...
;             PG8_STAGE(PG8_SB(0, 1), b2 + hstepB, voffB);
;             PG8_WAIT_V(6); PG8_BAR; PG8_MMA(1, 1, At, B1); PG8_BAR;
;             PG8_LDB(B0, 1, 0); PG8_SCHED; PG8_LDA(At, 1, 0); PG8_STAGE(PG8_SA(0, 1), a2 + hstepA, voffA);
;             PG8_WAIT_L(8); PG8_BAR; PG8_WAIT_L(0); PG8_MMA(0, 0, At, B0); PG8_BAR; PG8_SCHED;
;             PG8_LDB(B1, 1, 1); PG8_STAGE(PG8_SB(1, 0), b3, voffB);
;             PG8_BAR; PG8_WAIT_L(0); PG8_MMA(0, 1, At, B1); PG8_BAR;
;             PG8_LDA(At, 1, 1); PG8_STAGE(PG8_SA(1, 0), a3, voffA);
	s_add_u32 s40, s14, 0x80000
	s_addc_u32 s41, s15, 0
	s_add_i32 s39, s42, s23
	s_mov_b32 m0, s39
	v_lshl_add_u64 v[128:129], s[40:41], 0, v[156:157]
	global_load_lds_dwordx4 v[128:129], off
	s_add_i32 m0, s39, 0x2000
	v_lshl_add_u64 v[128:129], s[40:41], 0, v[158:159]
	global_load_lds_dwordx4 v[128:129], off
	s_waitcnt vmcnt(6)
	s_barrier
	v_mfma_f32_16x16x32_bf16 v[52:55], v[194:197], v[144:147], v[52:55]
	s_setprio 1
	v_mfma_f32_16x16x32_bf16 v[48:51], v[202:205], v[144:147], v[48:51]
	s_add_i32 s39, 0, 0x18000
	v_add_u32_e32 v140, s39, v170
	v_mfma_f32_16x16x32_bf16 v[36:39], v[194:197], v[166:169], v[36:39]
	v_mfma_f32_16x16x32_bf16 v[32:35], v[202:205], v[166:169], v[32:35]
	v_mfma_f32_16x16x32_bf16 v[20:23], v[194:197], v[178:181], v[20:23]
	v_mfma_f32_16x16x32_bf16 v[16:19], v[202:205], v[178:181], v[16:19]
	v_mfma_f32_16x16x32_bf16 v[4:7], v[194:197], v[186:189], v[4:7]
	v_mfma_f32_16x16x32_bf16 v[0:3], v[202:205], v[186:189], v[0:3]
	v_mfma_f32_16x16x32_bf16 v[52:55], v[198:201], v[148:151], v[52:55]
	v_mfma_f32_16x16x32_bf16 v[48:51], v[206:209], v[148:151], v[48:51]
	v_mfma_f32_16x16x32_bf16 v[36:39], v[198:201], v[174:177], v[36:39]
	v_mfma_f32_16x16x32_bf16 v[32:35], v[206:209], v[174:177], v[32:35]
	v_mfma_f32_16x16x32_bf16 v[20:23], v[198:201], v[182:185], v[20:23]
	v_mfma_f32_16x16x32_bf16 v[16:19], v[206:209], v[182:185], v[16:19]
	v_mfma_f32_16x16x32_bf16 v[4:7], v[198:201], v[190:193], v[4:7]
	s_setprio 0
	v_mfma_f32_16x16x32_bf16 v[0:3], v[206:209], v[190:193], v[0:3]
	s_barrier
	ds_read_b128 v[128:131], v140
	ds_read_b128 v[132:135], v140 offset:1024
	ds_read_b128 v[136:139], v140 offset:2048
	ds_read_b128 v[140:143], v140 offset:3072
	s_add_u32 s18, s18, 0x80000
	s_addc_u32 s19, s19, 0
	s_mov_b32 m0, s27
	v_lshl_add_u64 v[194:195], s[18:19], 0, v[156:157]
	ds_read_b128 v[144:147], v172 offset:32768
	ds_read_b128 v[148:151], v172 offset:33792
	ds_read_b128 v[166:169], v172 offset:34816
	ds_read_b128 v[174:177], v172 offset:35840
	ds_read_b128 v[178:181], v172 offset:36864
	ds_read_b128 v[182:185], v172 offset:37888
	ds_read_b128 v[186:189], v172 offset:38912
	ds_read_b128 v[190:193], v172 offset:39936
	global_load_lds_dwordx4 v[194:195], off
	s_mov_b32 m0, s28
	v_lshl_add_u64 v[194:195], s[18:19], 0, v[158:159]
	global_load_lds_dwordx4 v[194:195], off
	s_waitcnt lgkmcnt(8)
	s_barrier
	s_waitcnt lgkmcnt(0)
	v_mfma_f32_16x16x32_bf16 v[124:127], v[128:131], v[144:147], v[124:127]
	s_setprio 1
	v_mfma_f32_16x16x32_bf16 v[120:123], v[136:139], v[144:147], v[120:123]
	v_mfma_f32_16x16x32_bf16 v[108:111], v[128:131], v[166:169], v[108:111]
	v_mfma_f32_16x16x32_bf16 v[104:107], v[136:139], v[166:169], v[104:107]
	v_mfma_f32_16x16x32_bf16 v[92:95], v[128:131], v[178:181], v[92:95]
	v_mfma_f32_16x16x32_bf16 v[88:91], v[136:139], v[178:181], v[88:91]
	v_mfma_f32_16x16x32_bf16 v[76:79], v[128:131], v[186:189], v[76:79]
	v_mfma_f32_16x16x32_bf16 v[72:75], v[136:139], v[186:189], v[72:75]
	v_mfma_f32_16x16x32_bf16 v[124:127], v[132:135], v[148:151], v[124:127]
	v_mfma_f32_16x16x32_bf16 v[120:123], v[140:143], v[148:151], v[120:123]
	v_mfma_f32_16x16x32_bf16 v[108:111], v[132:135], v[174:177], v[108:111]
	v_mfma_f32_16x16x32_bf16 v[104:107], v[140:143], v[174:177], v[104:107]
	v_mfma_f32_16x16x32_bf16 v[92:95], v[132:135], v[182:185], v[92:95]
	v_mfma_f32_16x16x32_bf16 v[88:91], v[140:143], v[182:185], v[88:91]
	v_mfma_f32_16x16x32_bf16 v[76:79], v[132:135], v[190:193], v[76:79]
	s_setprio 0
	v_mfma_f32_16x16x32_bf16 v[72:75], v[140:143], v[190:193], v[72:75]
	s_barrier
	s_add_i32 s40, 0, 0x1c000
	s_add_u32 s18, s14, 0x4000
	s_addc_u32 s19, s15, 0
	s_add_i32 s39, s39, s23
	v_add_u32_e32 v152, s40, v170
	v_lshl_add_u64 v[210:211], s[18:19], 0, v[156:157]
	s_mov_b32 m0, s39
	ds_read_b128 v[194:197], v152
	ds_read_b128 v[198:201], v152 offset:1024
	ds_read_b128 v[202:205], v152 offset:2048
	ds_read_b128 v[206:209], v152 offset:3072
	global_load_lds_dwordx4 v[210:211], off
	s_add_i32 m0, s39, 0x2000
	v_lshl_add_u64 v[210:211], s[18:19], 0, v[158:159]
	global_load_lds_dwordx4 v[210:211], off
	s_barrier
	s_waitcnt lgkmcnt(0)
	v_mfma_f32_16x16x32_bf16 v[116:119], v[194:197], v[144:147], v[116:119]
	s_setprio 1
	v_mfma_f32_16x16x32_bf16 v[112:115], v[202:205], v[144:147], v[112:115]
	s_mov_b32 m0, s29
	v_lshl_add_u64 v[210:211], s[16:17], 0, v[156:157]
	v_mfma_f32_16x16x32_bf16 v[100:103], v[194:197], v[166:169], v[100:103]
	v_mfma_f32_16x16x32_bf16 v[96:99], v[202:205], v[166:169], v[96:99]
	v_mfma_f32_16x16x32_bf16 v[84:87], v[194:197], v[178:181], v[84:87]
	v_mfma_f32_16x16x32_bf16 v[80:83], v[202:205], v[178:181], v[80:83]
	v_mfma_f32_16x16x32_bf16 v[68:71], v[194:197], v[186:189], v[68:71]
	v_mfma_f32_16x16x32_bf16 v[64:67], v[202:205], v[186:189], v[64:67]
	v_mfma_f32_16x16x32_bf16 v[116:119], v[198:201], v[148:151], v[116:119]
	v_mfma_f32_16x16x32_bf16 v[112:115], v[206:209], v[148:151], v[112:115]
	v_mfma_f32_16x16x32_bf16 v[100:103], v[198:201], v[174:177], v[100:103]
	v_mfma_f32_16x16x32_bf16 v[96:99], v[206:209], v[174:177], v[96:99]
	v_mfma_f32_16x16x32_bf16 v[84:87], v[198:201], v[182:185], v[84:87]
	v_mfma_f32_16x16x32_bf16 v[80:83], v[206:209], v[182:185], v[80:83]
	v_mfma_f32_16x16x32_bf16 v[68:71], v[198:201], v[190:193], v[68:71]
	s_setprio 0
	v_mfma_f32_16x16x32_bf16 v[64:67], v[206:209], v[190:193], v[64:67]
	s_barrier
	ds_read_b128 v[144:147], v172 offset:49152
	ds_read_b128 v[148:151], v172 offset:50176
	ds_read_b128 v[166:169], v172 offset:51200
	ds_read_b128 v[174:177], v172 offset:52224
	ds_read_b128 v[178:181], v172 offset:53248
	ds_read_b128 v[182:185], v172 offset:54272
	ds_read_b128 v[186:189], v172 offset:55296
	ds_read_b128 v[190:193], v172 offset:56320
	global_load_lds_dwordx4 v[210:211], off
	s_mov_b32 m0, s30
	v_lshl_add_u64 v[210:211], s[16:17], 0, v[158:159]
	global_load_lds_dwordx4 v[210:211], off
	s_barrier
; #define PG8_STAGE(bufoff, gbase, voff) do { _Pragma("unroll") for (int _i = 0; _i < 2; ++_i) \
;         __builtin_amdgcn_global_load_lds((const unsigned*)((const char*)(gbase) + (voff)[_i]), (LAS unsigned*)(lds + (bufoff) + ldsw + _i * 8192), 16, 0, 0); } while (0)
; #define PG8_MMA(ai, bj, At, Bt) do { __builtin_amdgcn_s_setprio(1); _Pragma("unroll") for (int m = 0; m < 4; ++m) _Pragma("unroll") for (int n = 0; n < 2; ++n) _Pragma("unroll") for (int k = 0; k < 2; ++k) \
;         acc[ai][bj][m][n] = __builtin_amdgcn_mfma_f32_16x16x32_bf16(Bt[n][k], At[m][k], acc[ai][bj][m][n], 0, 0, 0); __builtin_amdgcn_s_setprio(0); } while (0)
; #define PG8_WAIT_V(n) asm volatile("s_waitcnt vmcnt(" #n ")" ::: "memory")
; #define PG8_WAIT_L(n) asm volatile("s_waitcnt lgkmcnt(" #n ")" ::: "memory")
; #define PG8_BAR __builtin_amdgcn_s_barrier()
; #define PG8_SCHED __builtin_amdgcn_sched_barrier(0)
; template <class Epi>
; __device__ __forceinline__ void gemm_phase(LAS unsigned char* lds, const Gemm g, const StaticOrder& S, const Epi& E) {
;     ...
;             PG8_BAR; PG8_WAIT_L(0); PG8_MMA(1, 0, At, B0); PG8_BAR; PG8_SCHED;
;             PG8_STAGE(PG8_SB(1, 1), b3 + hstepB, voffB);
;             PG8_WAIT_V(6); PG8_BAR; PG8_MMA(1, 1, At, B1); PG8_BAR;
;     __device__ __forceinline__ void operator()(const f32x4 (&acc)[2][2][4][2], const Unit& u, int wr, int wc, int fr, int fq) const {
;         const int row0 = u.pm * BM + wr * 64 + fr, j0 = wc * 16 + 4 * fq, colb = u.pn * BM + j0;
;         if (u.pn < 8) {
	s_waitcnt lgkmcnt(0)
	v_mfma_f32_16x16x32_bf16 v[60:63], v[128:131], v[144:147], v[60:63]
	s_setprio 1
	v_mfma_f32_16x16x32_bf16 v[56:59], v[136:139], v[144:147], v[56:59]
	v_mfma_f32_16x16x32_bf16 v[44:47], v[128:131], v[166:169], v[44:47]
	v_mfma_f32_16x16x32_bf16 v[40:43], v[136:139], v[166:169], v[40:43]
	v_mfma_f32_16x16x32_bf16 v[28:31], v[128:131], v[178:181], v[28:31]
	v_mfma_f32_16x16x32_bf16 v[24:27], v[136:139], v[178:181], v[24:27]
	v_mfma_f32_16x16x32_bf16 v[12:15], v[128:131], v[186:189], v[12:15]
	v_mfma_f32_16x16x32_bf16 v[8:11], v[136:139], v[186:189], v[8:11]
	v_mfma_f32_16x16x32_bf16 v[60:63], v[132:135], v[148:151], v[60:63]
	v_mfma_f32_16x16x32_bf16 v[56:59], v[140:143], v[148:151], v[56:59]
	v_mfma_f32_16x16x32_bf16 v[44:47], v[132:135], v[174:177], v[44:47]
	v_mfma_f32_16x16x32_bf16 v[40:43], v[140:143], v[174:177], v[40:43]
	v_mfma_f32_16x16x32_bf16 v[28:31], v[132:135], v[182:185], v[28:31]
	v_mfma_f32_16x16x32_bf16 v[24:27], v[140:143], v[182:185], v[24:27]
	v_mfma_f32_16x16x32_bf16 v[12:15], v[132:135], v[190:193], v[12:15]
	s_setprio 0
	v_mfma_f32_16x16x32_bf16 v[8:11], v[140:143], v[190:193], v[8:11]
	s_barrier
	s_add_u32 s14, s14, 0x84000
	s_addc_u32 s15, s15, 0
	s_add_i32 s16, s40, s23
	s_mov_b32 m0, s16
	v_lshl_add_u64 v[128:129], s[14:15], 0, v[156:157]
	global_load_lds_dwordx4 v[128:129], off
	s_add_i32 m0, s16, 0x2000
	v_lshl_add_u64 v[128:129], s[14:15], 0, v[158:159]
	global_load_lds_dwordx4 v[128:129], off
	s_waitcnt vmcnt(6)
	s_barrier
	v_mfma_f32_16x16x32_bf16 v[52:55], v[194:197], v[144:147], v[52:55]
	s_setprio 1
	v_mfma_f32_16x16x32_bf16 v[48:51], v[202:205], v[144:147], v[48:51]
	s_add_i32 s38, s38, 2
	s_add_u32 s12, s12, 0x8000
	s_addc_u32 s13, s13, 0
	s_add_u32 s36, s36, 0x8000
	s_addc_u32 s37, s37, 0
	v_mfma_f32_16x16x32_bf16 v[36:39], v[194:197], v[166:169], v[36:39]
	v_mfma_f32_16x16x32_bf16 v[32:35], v[202:205], v[166:169], v[32:35]
	v_mfma_f32_16x16x32_bf16 v[20:23], v[194:197], v[178:181], v[20:23]
	v_mfma_f32_16x16x32_bf16 v[16:19], v[202:205], v[178:181], v[16:19]
	v_mfma_f32_16x16x32_bf16 v[4:7], v[194:197], v[186:189], v[4:7]
	v_mfma_f32_16x16x32_bf16 v[0:3], v[202:205], v[186:189], v[0:3]
	v_mfma_f32_16x16x32_bf16 v[52:55], v[198:201], v[148:151], v[52:55]
	v_mfma_f32_16x16x32_bf16 v[48:51], v[206:209], v[148:151], v[48:51]
	v_mfma_f32_16x16x32_bf16 v[36:39], v[198:201], v[174:177], v[36:39]
	v_mfma_f32_16x16x32_bf16 v[32:35], v[206:209], v[174:177], v[32:35]
	v_mfma_f32_16x16x32_bf16 v[20:23], v[198:201], v[182:185], v[20:23]
	v_mfma_f32_16x16x32_bf16 v[16:19], v[206:209], v[182:185], v[16:19]
	v_mfma_f32_16x16x32_bf16 v[4:7], v[198:201], v[190:193], v[4:7]
	s_cmp_gt_u32 s38, 29
	s_setprio 0
	v_mfma_f32_16x16x32_bf16 v[0:3], v[206:209], v[190:193], v[0:3]
	s_barrier
	s_cbranch_scc0 .LBB0_247
	v_lshl_add_u32 v177, s10, 8, v165
	v_lshl_or_b32 v152, s34, 8, v171
	s_mov_b64 s[10:11], -1
	s_cmp_lt_i32 s34, 8
	v_or_b32_e32 v180, 16, v177
	v_or_b32_e32 v179, 32, v177
	v_or_b32_e32 v178, 48, v177
	v_add_u32_e32 v176, 0x80, v177
	v_add_u32_e32 v175, 0x90, v177
	v_add_u32_e32 v174, 0xa0, v177
	v_add_u32_e32 v173, 0xb0, v177
	s_cbranch_scc1 .LBB0_250
; __device__ __forceinline__ unsigned cvt_pk_bf16(float lo, float hi) { unsigned r; asm volatile("v_cvt_pk_bf16_f32 %0, %1, %2" : "=v"(r) : "v"(lo), "v"(hi)); return r; }
;     __device__ __forceinline__ void operator()(const f32x4 (&acc)[2][2][4][2], const Unit& u, int wr, int wc, int fr, int fq) const {
;     ...
; #pragma unroll
;             for (int ai = 0; ai < 2; ++ai)
; #pragma unroll
;                 for (int m = 0; m < 4; ++m) {
;                     const int row = row0 + ai * HALF + m * 16;
;                     bf16_t* rowp = O + (size_t)row * DIN + colb;
; #pragma unroll
;                     for (int bj = 0; bj < 2; ++bj) {
;                         const f32x4 o1 = acc[ai][bj][m][0], o2 = acc[ai][bj][m][1];
;                         u32x2 w1, w2; w1.x = cvt_pk_bf16(o1[0], o1[1]); w1.y = cvt_pk_bf16(o1[2], o1[3]); w2.x = cvt_pk_bf16(o2[0], o2[1]); w2.y = cvt_pk_bf16(o2[2], o2[3]);
;                         *(u32x2*)(rowp + bj * HALF) = w1; *(u32x2*)(rowp + bj * HALF + 64) = w2;
;                     }
;                 }
	v_readlane_b32 s10, v252, 57
	v_readlane_b32 s11, v252, 58
	s_movk_i32 s3, 0x3000
	v_lshlrev_b64 v[130:131], 1, v[152:153]
	v_mov_b64_e32 v[128:129], s[10:11]
	v_mad_i64_i32 v[132:133], s[10:11], v177, s3, v[128:129]
	v_lshl_add_u64 v[132:133], v[132:133], 0, v[130:131]
	v_cvt_pk_bf16_f32 v134, v124, v125
	v_cvt_pk_bf16_f32 v135, v126, v127
	v_cvt_pk_bf16_f32 v136, v120, v121
	v_cvt_pk_bf16_f32 v137, v122, v123
	global_store_dwordx2 v[132:133], v[134:135], off
	global_store_dwordx2 v[132:133], v[136:137], off offset:128
	v_cvt_pk_bf16_f32 v134, v116, v117
	v_cvt_pk_bf16_f32 v135, v118, v119
	v_cvt_pk_bf16_f32 v136, v112, v113
	v_cvt_pk_bf16_f32 v137, v114, v115
	global_store_dwordx2 v[132:133], v[134:135], off offset:256
	global_store_dwordx2 v[132:133], v[136:137], off offset:384
	v_mad_i64_i32 v[132:133], s[10:11], v180, s3, v[128:129]
	v_lshl_add_u64 v[132:133], v[132:133], 0, v[130:131]
	v_cvt_pk_bf16_f32 v134, v108, v109
	v_cvt_pk_bf16_f32 v135, v110, v111
	v_cvt_pk_bf16_f32 v136, v104, v105
	v_cvt_pk_bf16_f32 v137, v106, v107
	global_store_dwordx2 v[132:133], v[134:135], off
	global_store_dwordx2 v[132:133], v[136:137], off offset:128
	v_cvt_pk_bf16_f32 v134, v100, v101
	v_cvt_pk_bf16_f32 v135, v102, v103
	v_cvt_pk_bf16_f32 v136, v96, v97
	v_cvt_pk_bf16_f32 v137, v98, v99
	global_store_dwordx2 v[132:133], v[134:135], off offset:256
	global_store_dwordx2 v[132:133], v[136:137], off offset:384
	v_mad_i64_i32 v[132:133], s[10:11], v179, s3, v[128:129]
	v_lshl_add_u64 v[132:133], v[132:133], 0, v[130:131]
	v_cvt_pk_bf16_f32 v134, v92, v93
	v_cvt_pk_bf16_f32 v135, v94, v95
	v_cvt_pk_bf16_f32 v136, v88, v89
	v_cvt_pk_bf16_f32 v137, v90, v91
	global_store_dwordx2 v[132:133], v[134:135], off
	global_store_dwordx2 v[132:133], v[136:137], off offset:128
	v_cvt_pk_bf16_f32 v134, v84, v85
	v_cvt_pk_bf16_f32 v135, v86, v87
	v_cvt_pk_bf16_f32 v136, v80, v81
	v_cvt_pk_bf16_f32 v137, v82, v83
	global_store_dwordx2 v[132:133], v[134:135], off offset:256
	global_store_dwordx2 v[132:133], v[136:137], off offset:384
	v_mad_i64_i32 v[132:133], s[10:11], v178, s3, v[128:129]
	v_lshl_add_u64 v[132:133], v[132:133], 0, v[130:131]
	v_cvt_pk_bf16_f32 v134, v76, v77
	v_cvt_pk_bf16_f32 v135, v78, v79
	v_cvt_pk_bf16_f32 v136, v72, v73
	v_cvt_pk_bf16_f32 v137, v74, v75
	global_store_dwordx2 v[132:133], v[134:135], off
	global_store_dwordx2 v[132:133], v[136:137], off offset:128
	v_cvt_pk_bf16_f32 v134, v68, v69
	v_cvt_pk_bf16_f32 v135, v70, v71
	v_cvt_pk_bf16_f32 v136, v64, v65
	v_cvt_pk_bf16_f32 v137, v66, v67
	global_store_dwordx2 v[132:133], v[134:135], off offset:256
	global_store_dwordx2 v[132:133], v[136:137], off offset:384
	v_mad_i64_i32 v[132:133], s[10:11], v176, s3, v[128:129]
	v_lshl_add_u64 v[132:133], v[132:133], 0, v[130:131]
	v_cvt_pk_bf16_f32 v134, v60, v61
	v_cvt_pk_bf16_f32 v135, v62, v63
	v_cvt_pk_bf16_f32 v136, v56, v57
	v_cvt_pk_bf16_f32 v137, v58, v59
	global_store_dwordx2 v[132:133], v[134:135], off
	global_store_dwordx2 v[132:133], v[136:137], off offset:128
	v_cvt_pk_bf16_f32 v134, v52, v53
	v_cvt_pk_bf16_f32 v135, v54, v55
	v_cvt_pk_bf16_f32 v136, v48, v49
	v_cvt_pk_bf16_f32 v137, v50, v51
	global_store_dwordx2 v[132:133], v[134:135], off offset:256
	global_store_dwordx2 v[132:133], v[136:137], off offset:384
	v_mad_i64_i32 v[132:133], s[10:11], v175, s3, v[128:129]
	v_lshl_add_u64 v[132:133], v[132:133], 0, v[130:131]
	v_cvt_pk_bf16_f32 v134, v44, v45
	v_cvt_pk_bf16_f32 v135, v46, v47
	v_cvt_pk_bf16_f32 v136, v40, v41
	v_cvt_pk_bf16_f32 v137, v42, v43
	global_store_dwordx2 v[132:133], v[134:135], off
	global_store_dwordx2 v[132:133], v[136:137], off offset:128
	v_cvt_pk_bf16_f32 v134, v36, v37
	v_cvt_pk_bf16_f32 v135, v38, v39
	v_cvt_pk_bf16_f32 v136, v32, v33
	v_cvt_pk_bf16_f32 v137, v34, v35
	global_store_dwordx2 v[132:133], v[134:135], off offset:256
	global_store_dwordx2 v[132:133], v[136:137], off offset:384
	v_mad_i64_i32 v[132:133], s[10:11], v174, s3, v[128:129]
	v_lshl_add_u64 v[132:133], v[132:133], 0, v[130:131]
	v_cvt_pk_bf16_f32 v134, v28, v29
	v_cvt_pk_bf16_f32 v135, v30, v31
	v_cvt_pk_bf16_f32 v136, v24, v25
	v_cvt_pk_bf16_f32 v137, v26, v27
	global_store_dwordx2 v[132:133], v[134:135], off
	global_store_dwordx2 v[132:133], v[136:137], off offset:128
	v_cvt_pk_bf16_f32 v134, v20, v21
	v_cvt_pk_bf16_f32 v135, v22, v23
	v_mad_i64_i32 v[128:129], s[10:11], v173, s3, v[128:129]
	v_cvt_pk_bf16_f32 v136, v16, v17
	v_cvt_pk_bf16_f32 v137, v18, v19
	global_store_dwordx2 v[132:133], v[134:135], off offset:256
	global_store_dwordx2 v[132:133], v[136:137], off offset:384
	v_lshl_add_u64 v[128:129], v[128:129], 0, v[130:131]
	v_cvt_pk_bf16_f32 v130, v12, v13
	v_cvt_pk_bf16_f32 v131, v14, v15
	v_cvt_pk_bf16_f32 v132, v8, v9
	v_cvt_pk_bf16_f32 v133, v10, v11
	s_mov_b64 s[10:11], 0
	global_store_dwordx2 v[128:129], v[130:131], off
	global_store_dwordx2 v[128:129], v[132:133], off offset:128
	v_cvt_pk_bf16_f32 v130, v4, v5
	v_cvt_pk_bf16_f32 v131, v6, v7
	v_cvt_pk_bf16_f32 v132, v0, v1
	v_cvt_pk_bf16_f32 v133, v2, v3
